# GEMM mainloops (GEMM1, GLU, out, up, down): per-segment s_setprio flips removed, one static priority raise for waves 0-3 per tile K loop
# baseline (speedup 1.0000x reference)
.LBB0_31:
	s_add_u32 s40, s12, 0x100
	v_mov_b32_e32 v0, 0
	s_addc_u32 s41, s13, 0
	s_mov_b32 s42, -2
	v_mov_b32_e32 v1, v0
	v_mov_b32_e32 v2, v0
	v_mov_b32_e32 v3, v0
	v_mov_b32_e32 v26, v0
	v_mov_b32_e32 v27, v0
	v_mov_b32_e32 v28, v0
	v_mov_b32_e32 v29, v0
	v_mov_b32_e32 v4, v0
	v_mov_b32_e32 v5, v0
	v_mov_b32_e32 v6, v0
	v_mov_b32_e32 v7, v0
	v_mov_b32_e32 v34, v0
	v_mov_b32_e32 v35, v0
	v_mov_b32_e32 v36, v0
	v_mov_b32_e32 v37, v0
	v_mov_b32_e32 v8, v0
	v_mov_b32_e32 v9, v0
	v_mov_b32_e32 v10, v0
	v_mov_b32_e32 v11, v0
	v_mov_b32_e32 v38, v0
	v_mov_b32_e32 v39, v0
	v_mov_b32_e32 v40, v0
	v_mov_b32_e32 v41, v0
	v_mov_b32_e32 v12, v0
	v_mov_b32_e32 v13, v0
	v_mov_b32_e32 v14, v0
	v_mov_b32_e32 v15, v0
	v_mov_b32_e32 v46, v0
	v_mov_b32_e32 v47, v0
	v_mov_b32_e32 v48, v0
	v_mov_b32_e32 v49, v0
	v_mov_b32_e32 v62, v0
	v_mov_b32_e32 v63, v0
	v_mov_b32_e32 v64, v0
	v_mov_b32_e32 v65, v0
	v_mov_b32_e32 v98, v0
	v_mov_b32_e32 v99, v0
	v_mov_b32_e32 v100, v0
	v_mov_b32_e32 v101, v0
	s_waitcnt vmcnt(0)
	v_mov_b32_e32 v70, v0
	v_mov_b32_e32 v71, v0
	v_mov_b32_e32 v72, v0
	v_mov_b32_e32 v73, v0
	v_mov_b32_e32 v102, v0
	v_mov_b32_e32 v103, v0
	v_mov_b32_e32 v104, v0
	v_mov_b32_e32 v105, v0
	v_mov_b32_e32 v74, v0
	v_mov_b32_e32 v75, v0
	v_mov_b32_e32 v76, v0
	v_mov_b32_e32 v77, v0
	v_mov_b32_e32 v106, v0
	v_mov_b32_e32 v107, v0
	v_mov_b32_e32 v108, v0
	v_mov_b32_e32 v109, v0
	v_mov_b32_e32 v78, v0
	v_mov_b32_e32 v79, v0
	v_mov_b32_e32 v80, v0
	v_mov_b32_e32 v81, v0
	v_mov_b32_e32 v110, v0
	v_mov_b32_e32 v111, v0
	v_mov_b32_e32 v112, v0
	v_mov_b32_e32 v113, v0
	v_mov_b32_e32 v18, v0
	v_mov_b32_e32 v19, v0
	v_mov_b32_e32 v20, v0
	v_mov_b32_e32 v21, v0
	v_mov_b32_e32 v50, v0
	v_mov_b32_e32 v51, v0
	v_mov_b32_e32 v52, v0
	v_mov_b32_e32 v53, v0
	v_mov_b32_e32 v22, v0
	v_mov_b32_e32 v23, v0
	v_mov_b32_e32 v24, v0
	v_mov_b32_e32 v25, v0
	v_mov_b32_e32 v54, v0
	v_mov_b32_e32 v55, v0
	v_mov_b32_e32 v56, v0
	v_mov_b32_e32 v57, v0
	v_mov_b32_e32 v30, v0
	v_mov_b32_e32 v31, v0
	v_mov_b32_e32 v32, v0
	v_mov_b32_e32 v33, v0
	v_mov_b32_e32 v58, v0
	v_mov_b32_e32 v59, v0
	v_mov_b32_e32 v60, v0
	v_mov_b32_e32 v61, v0
	v_mov_b32_e32 v42, v0
	v_mov_b32_e32 v43, v0
	v_mov_b32_e32 v44, v0
	v_mov_b32_e32 v45, v0
	v_mov_b32_e32 v66, v0
	v_mov_b32_e32 v67, v0
	v_mov_b32_e32 v68, v0
	v_mov_b32_e32 v69, v0
	v_mov_b32_e32 v82, v0
	v_mov_b32_e32 v83, v0
	v_mov_b32_e32 v84, v0
	v_mov_b32_e32 v85, v0
	v_mov_b32_e32 v114, v0
	v_mov_b32_e32 v115, v0
	v_mov_b32_e32 v116, v0
	v_mov_b32_e32 v117, v0
	v_mov_b32_e32 v86, v0
	v_mov_b32_e32 v87, v0
	v_mov_b32_e32 v88, v0
	v_mov_b32_e32 v89, v0
	v_mov_b32_e32 v118, v0
	v_mov_b32_e32 v119, v0
	v_mov_b32_e32 v120, v0
	v_mov_b32_e32 v121, v0
	v_mov_b32_e32 v90, v0
	v_mov_b32_e32 v91, v0
	v_mov_b32_e32 v92, v0
	v_mov_b32_e32 v93, v0
	v_mov_b32_e32 v122, v0
	v_mov_b32_e32 v123, v0
	v_mov_b32_e32 v124, v0
	v_mov_b32_e32 v125, v0
	v_mov_b32_e32 v94, v0
	v_mov_b32_e32 v95, v0
	v_mov_b32_e32 v96, v0
	v_mov_b32_e32 v97, v0
	v_mov_b32_e32 v126, v0
	v_mov_b32_e32 v127, v0
	v_mov_b32_e32 v128, v0
	v_mov_b32_e32 v129, v0
	v_readlane_b32 s100, v253, 1
	s_cmp_ge_u32 s100, 4
	s_cbranch_scc1 .Lprio_1
	s_setprio 1
.Lprio_1:
.LBB0_32:
	s_add_u32 s12, s10, 0x100
	s_addc_u32 s13, s11, 0
	s_add_i32 s33, 0, 0x10000
	s_cmpk_eq_i32 s42, 0x52
	s_cselect_b32 s17, s1, s13
	s_cselect_b32 s16, s0, s12
	s_cselect_b32 s15, s9, s41
	s_cselect_b32 s14, s8, s40
	s_add_i32 s43, 0, 0x14000
	v_add_u32_e32 v142, s33, v207
	v_add_u32_e32 v158, s43, v207
	ds_read_b128 v[130:133], v142
	ds_read_b128 v[134:137], v142 offset:1024
	ds_read_b128 v[138:141], v142 offset:2048
	ds_read_b128 v[142:145], v142 offset:3072
	ds_read_b128 v[146:149], v158
	ds_read_b128 v[150:153], v158 offset:1024
	ds_read_b128 v[154:157], v158 offset:2048
	ds_read_b128 v[158:161], v158 offset:3072
	v_lshl_add_u64 v[204:205], s[10:11], 0, v[180:181]
	s_add_i32 m0, s23, 0xc000
	ds_read_b128 v[162:165], v208
	ds_read_b128 v[166:169], v208 offset:1024
	ds_read_b128 v[170:173], v208 offset:2048
	ds_read_b128 v[184:187], v208 offset:3072
	ds_read_b128 v[188:191], v208 offset:4096
	ds_read_b128 v[192:195], v208 offset:5120
	ds_read_b128 v[196:199], v208 offset:6144
	ds_read_b128 v[200:203], v208 offset:7168
	global_load_lds_dwordx4 v[204:205], off
	v_lshl_add_u64 v[204:205], s[10:11], 0, v[182:183]
	s_add_i32 m0, s23, 0xe000
	s_nop 0
	global_load_lds_dwordx4 v[204:205], off
	s_waitcnt vmcnt(8)
	s_waitcnt lgkmcnt(0)
	s_barrier
	s_waitcnt lgkmcnt(0)
	v_mfma_f32_16x16x32_bf16 v[126:129], v[130:133], v[162:165], v[126:129]
	v_mfma_f32_16x16x32_bf16 v[94:97], v[138:141], v[162:165], v[94:97]
	v_mfma_f32_16x16x32_bf16 v[122:125], v[130:133], v[170:173], v[122:125]
	v_mfma_f32_16x16x32_bf16 v[90:93], v[138:141], v[170:173], v[90:93]
	v_mfma_f32_16x16x32_bf16 v[118:121], v[130:133], v[188:191], v[118:121]
	v_mfma_f32_16x16x32_bf16 v[86:89], v[138:141], v[188:191], v[86:89]
	v_mfma_f32_16x16x32_bf16 v[114:117], v[130:133], v[196:199], v[114:117]
	v_mfma_f32_16x16x32_bf16 v[82:85], v[138:141], v[196:199], v[82:85]
	v_mfma_f32_16x16x32_bf16 v[126:129], v[134:137], v[166:169], v[126:129]
	v_mfma_f32_16x16x32_bf16 v[94:97], v[142:145], v[166:169], v[94:97]
	v_mfma_f32_16x16x32_bf16 v[122:125], v[134:137], v[184:187], v[122:125]
	v_mfma_f32_16x16x32_bf16 v[90:93], v[142:145], v[184:187], v[90:93]
	v_mfma_f32_16x16x32_bf16 v[118:121], v[134:137], v[192:195], v[118:121]
	v_mfma_f32_16x16x32_bf16 v[86:89], v[142:145], v[192:195], v[86:89]
	v_mfma_f32_16x16x32_bf16 v[114:117], v[134:137], v[200:203], v[114:117]
	v_mfma_f32_16x16x32_bf16 v[82:85], v[142:145], v[200:203], v[82:85]
	v_mfma_f32_16x16x32_bf16 v[66:69], v[146:149], v[162:165], v[66:69]
	v_mfma_f32_16x16x32_bf16 v[42:45], v[154:157], v[162:165], v[42:45]
	v_mfma_f32_16x16x32_bf16 v[58:61], v[146:149], v[170:173], v[58:61]
	v_mfma_f32_16x16x32_bf16 v[30:33], v[154:157], v[170:173], v[30:33]
	v_mfma_f32_16x16x32_bf16 v[54:57], v[146:149], v[188:191], v[54:57]
	v_mfma_f32_16x16x32_bf16 v[22:25], v[154:157], v[188:191], v[22:25]
	v_mfma_f32_16x16x32_bf16 v[50:53], v[146:149], v[196:199], v[50:53]
	v_mfma_f32_16x16x32_bf16 v[18:21], v[154:157], v[196:199], v[18:21]
	v_mfma_f32_16x16x32_bf16 v[66:69], v[150:153], v[166:169], v[66:69]
	v_mfma_f32_16x16x32_bf16 v[42:45], v[158:161], v[166:169], v[42:45]
	v_mfma_f32_16x16x32_bf16 v[58:61], v[150:153], v[184:187], v[58:61]
	v_mfma_f32_16x16x32_bf16 v[30:33], v[158:161], v[184:187], v[30:33]
	v_mfma_f32_16x16x32_bf16 v[54:57], v[150:153], v[192:195], v[54:57]
	v_mfma_f32_16x16x32_bf16 v[22:25], v[158:161], v[192:195], v[22:25]
	v_mfma_f32_16x16x32_bf16 v[50:53], v[150:153], v[200:203], v[50:53]
	v_mfma_f32_16x16x32_bf16 v[18:21], v[158:161], v[200:203], v[18:21]
	s_barrier
	s_add_i32 s10, s33, s22
	v_lshl_add_u64 v[204:205], s[14:15], 0, v[178:179]
	s_mov_b32 m0, s10
	ds_read_b128 v[162:165], v208 offset:16384
	ds_read_b128 v[166:169], v208 offset:17408
	ds_read_b128 v[170:173], v208 offset:18432
	ds_read_b128 v[184:187], v208 offset:19456
	ds_read_b128 v[188:191], v208 offset:20480
	ds_read_b128 v[192:195], v208 offset:21504
	ds_read_b128 v[196:199], v208 offset:22528
	ds_read_b128 v[200:203], v208 offset:23552
	global_load_lds_dwordx4 v[204:205], off
	s_add_i32 m0, s10, 0x2000
	s_add_u32 s10, s14, 0x158000
	v_lshl_add_u64 v[210:211], s[14:15], 0, v[176:177]
	s_addc_u32 s11, s15, 0
	s_add_i32 s33, s43, s22
	global_load_lds_dwordx4 v[210:211], off
	v_lshl_add_u64 v[212:213], s[10:11], 0, v[178:179]
	s_mov_b32 m0, s33
	v_lshl_add_u64 v[214:215], s[16:17], 0, v[176:177]
	global_load_lds_dwordx4 v[212:213], off
	v_lshl_add_u64 v[212:213], s[10:11], 0, v[176:177]
	s_add_i32 m0, s33, 0x2000
	s_nop 0
	global_load_lds_dwordx4 v[212:213], off
	v_lshl_add_u64 v[212:213], s[16:17], 0, v[178:179]
	s_mov_b32 m0, s23
	s_nop 0
	global_load_lds_dwordx4 v[212:213], off
	s_mov_b32 m0, s24
	s_nop 0
	global_load_lds_dwordx4 v[214:215], off
	s_waitcnt vmcnt(8)
	s_waitcnt lgkmcnt(0)
	s_barrier
	s_waitcnt lgkmcnt(0)
	v_mfma_f32_16x16x32_bf16 v[110:113], v[130:133], v[162:165], v[110:113]
	v_mfma_f32_16x16x32_bf16 v[78:81], v[138:141], v[162:165], v[78:81]
	v_mfma_f32_16x16x32_bf16 v[106:109], v[130:133], v[170:173], v[106:109]
	v_mfma_f32_16x16x32_bf16 v[74:77], v[138:141], v[170:173], v[74:77]
	v_mfma_f32_16x16x32_bf16 v[102:105], v[130:133], v[188:191], v[102:105]
	v_mfma_f32_16x16x32_bf16 v[70:73], v[138:141], v[188:191], v[70:73]
	v_mfma_f32_16x16x32_bf16 v[98:101], v[130:133], v[196:199], v[98:101]
	v_mfma_f32_16x16x32_bf16 v[62:65], v[138:141], v[196:199], v[62:65]
	v_mfma_f32_16x16x32_bf16 v[110:113], v[134:137], v[166:169], v[110:113]
	v_mfma_f32_16x16x32_bf16 v[78:81], v[142:145], v[166:169], v[78:81]
	v_mfma_f32_16x16x32_bf16 v[106:109], v[134:137], v[184:187], v[106:109]
	v_mfma_f32_16x16x32_bf16 v[74:77], v[142:145], v[184:187], v[74:77]
	v_mfma_f32_16x16x32_bf16 v[102:105], v[134:137], v[192:195], v[102:105]
	v_mfma_f32_16x16x32_bf16 v[70:73], v[142:145], v[192:195], v[70:73]
	v_mfma_f32_16x16x32_bf16 v[98:101], v[134:137], v[200:203], v[98:101]
	v_mfma_f32_16x16x32_bf16 v[62:65], v[142:145], v[200:203], v[62:65]
	v_mfma_f32_16x16x32_bf16 v[46:49], v[146:149], v[162:165], v[46:49]
	v_mfma_f32_16x16x32_bf16 v[12:15], v[154:157], v[162:165], v[12:15]
	v_mfma_f32_16x16x32_bf16 v[38:41], v[146:149], v[170:173], v[38:41]
	v_mfma_f32_16x16x32_bf16 v[8:11], v[154:157], v[170:173], v[8:11]
	v_mfma_f32_16x16x32_bf16 v[34:37], v[146:149], v[188:191], v[34:37]
	v_mfma_f32_16x16x32_bf16 v[4:7], v[154:157], v[188:191], v[4:7]
	v_mfma_f32_16x16x32_bf16 v[26:29], v[146:149], v[196:199], v[26:29]
	v_mfma_f32_16x16x32_bf16 v[0:3], v[154:157], v[196:199], v[0:3]
	v_mfma_f32_16x16x32_bf16 v[46:49], v[150:153], v[166:169], v[46:49]
	v_mfma_f32_16x16x32_bf16 v[12:15], v[158:161], v[166:169], v[12:15]
	v_mfma_f32_16x16x32_bf16 v[38:41], v[150:153], v[184:187], v[38:41]
	v_mfma_f32_16x16x32_bf16 v[8:11], v[158:161], v[184:187], v[8:11]
	v_mfma_f32_16x16x32_bf16 v[34:37], v[150:153], v[192:195], v[34:37]
	v_mfma_f32_16x16x32_bf16 v[4:7], v[158:161], v[192:195], v[4:7]
	v_mfma_f32_16x16x32_bf16 v[26:29], v[150:153], v[200:203], v[26:29]
	v_mfma_f32_16x16x32_bf16 v[0:3], v[158:161], v[200:203], v[0:3]
	s_barrier
	s_add_i32 s33, 0, 0x18000
	s_add_i32 s43, 0, 0x1c000
	v_add_u32_e32 v142, s33, v207
	v_add_u32_e32 v158, s43, v207
	ds_read_b128 v[130:133], v142
	ds_read_b128 v[134:137], v142 offset:1024
	ds_read_b128 v[138:141], v142 offset:2048
	ds_read_b128 v[142:145], v142 offset:3072
	ds_read_b128 v[146:149], v158
	ds_read_b128 v[150:153], v158 offset:1024
	ds_read_b128 v[154:157], v158 offset:2048
	ds_read_b128 v[158:161], v158 offset:3072
	s_add_u32 s10, s16, 0x158000
	s_addc_u32 s11, s17, 0
	s_mov_b32 m0, s25
	v_lshl_add_u64 v[222:223], s[10:11], 0, v[178:179]
	ds_read_b128 v[162:165], v208 offset:32768
	ds_read_b128 v[166:169], v208 offset:33792
	ds_read_b128 v[170:173], v208 offset:34816
	ds_read_b128 v[184:187], v208 offset:35840
	ds_read_b128 v[188:191], v208 offset:36864
	ds_read_b128 v[192:195], v208 offset:37888
	ds_read_b128 v[196:199], v208 offset:38912
	ds_read_b128 v[200:203], v208 offset:39936
	global_load_lds_dwordx4 v[222:223], off
	v_lshl_add_u64 v[222:223], s[10:11], 0, v[176:177]
	s_mov_b32 m0, s26
	s_nop 0
	global_load_lds_dwordx4 v[222:223], off
	s_waitcnt vmcnt(8)
	s_waitcnt lgkmcnt(0)
	s_barrier
	s_waitcnt lgkmcnt(0)
	v_mfma_f32_16x16x32_bf16 v[126:129], v[130:133], v[162:165], v[126:129]
	v_mfma_f32_16x16x32_bf16 v[94:97], v[138:141], v[162:165], v[94:97]
	v_mfma_f32_16x16x32_bf16 v[122:125], v[130:133], v[170:173], v[122:125]
	v_mfma_f32_16x16x32_bf16 v[90:93], v[138:141], v[170:173], v[90:93]
	v_mfma_f32_16x16x32_bf16 v[118:121], v[130:133], v[188:191], v[118:121]
	v_mfma_f32_16x16x32_bf16 v[86:89], v[138:141], v[188:191], v[86:89]
	v_mfma_f32_16x16x32_bf16 v[114:117], v[130:133], v[196:199], v[114:117]
	v_mfma_f32_16x16x32_bf16 v[82:85], v[138:141], v[196:199], v[82:85]
	v_mfma_f32_16x16x32_bf16 v[126:129], v[134:137], v[166:169], v[126:129]
	v_mfma_f32_16x16x32_bf16 v[94:97], v[142:145], v[166:169], v[94:97]
	v_mfma_f32_16x16x32_bf16 v[122:125], v[134:137], v[184:187], v[122:125]
	v_mfma_f32_16x16x32_bf16 v[90:93], v[142:145], v[184:187], v[90:93]
	v_mfma_f32_16x16x32_bf16 v[118:121], v[134:137], v[192:195], v[118:121]
	v_mfma_f32_16x16x32_bf16 v[86:89], v[142:145], v[192:195], v[86:89]
	v_mfma_f32_16x16x32_bf16 v[114:117], v[134:137], v[200:203], v[114:117]
	v_mfma_f32_16x16x32_bf16 v[82:85], v[142:145], v[200:203], v[82:85]
	v_mfma_f32_16x16x32_bf16 v[66:69], v[146:149], v[162:165], v[66:69]
	v_mfma_f32_16x16x32_bf16 v[42:45], v[154:157], v[162:165], v[42:45]
	v_mfma_f32_16x16x32_bf16 v[58:61], v[146:149], v[170:173], v[58:61]
	v_mfma_f32_16x16x32_bf16 v[30:33], v[154:157], v[170:173], v[30:33]
	v_mfma_f32_16x16x32_bf16 v[54:57], v[146:149], v[188:191], v[54:57]
	v_mfma_f32_16x16x32_bf16 v[22:25], v[154:157], v[188:191], v[22:25]
	v_mfma_f32_16x16x32_bf16 v[50:53], v[146:149], v[196:199], v[50:53]
	v_mfma_f32_16x16x32_bf16 v[18:21], v[154:157], v[196:199], v[18:21]
	v_mfma_f32_16x16x32_bf16 v[66:69], v[150:153], v[166:169], v[66:69]
	v_mfma_f32_16x16x32_bf16 v[42:45], v[158:161], v[166:169], v[42:45]
	v_mfma_f32_16x16x32_bf16 v[58:61], v[150:153], v[184:187], v[58:61]
	v_mfma_f32_16x16x32_bf16 v[30:33], v[158:161], v[184:187], v[30:33]
	v_mfma_f32_16x16x32_bf16 v[54:57], v[150:153], v[192:195], v[54:57]
	v_mfma_f32_16x16x32_bf16 v[22:25], v[158:161], v[192:195], v[22:25]
	v_mfma_f32_16x16x32_bf16 v[50:53], v[150:153], v[200:203], v[50:53]
	v_mfma_f32_16x16x32_bf16 v[18:21], v[158:161], v[200:203], v[18:21]
	s_barrier
	s_add_i32 s10, s33, s22
	v_lshl_add_u64 v[204:205], v[204:205], 0, s[56:57]
	s_mov_b32 m0, s10
	ds_read_b128 v[162:165], v208 offset:49152
	ds_read_b128 v[166:169], v208 offset:50176
	ds_read_b128 v[170:173], v208 offset:51200
	ds_read_b128 v[184:187], v208 offset:52224
	ds_read_b128 v[188:191], v208 offset:53248
	ds_read_b128 v[192:195], v208 offset:54272
	ds_read_b128 v[196:199], v208 offset:55296
	ds_read_b128 v[200:203], v208 offset:56320
	global_load_lds_dwordx4 v[204:205], off
	s_add_i32 m0, s10, 0x2000
	s_add_u32 s10, s14, 0x158080
	v_lshl_add_u64 v[204:205], v[210:211], 0, s[56:57]
	s_addc_u32 s11, s15, 0
	s_add_i32 s14, s43, s22
	global_load_lds_dwordx4 v[204:205], off
	v_lshl_add_u64 v[204:205], s[10:11], 0, v[178:179]
	s_mov_b32 m0, s14
	s_nop 0
	global_load_lds_dwordx4 v[204:205], off
	v_lshl_add_u64 v[204:205], s[10:11], 0, v[176:177]
	s_add_i32 m0, s14, 0x2000
	s_nop 0
	global_load_lds_dwordx4 v[204:205], off
	v_lshl_add_u64 v[204:205], v[212:213], 0, s[56:57]
	s_mov_b32 m0, s31
	s_nop 0
	global_load_lds_dwordx4 v[204:205], off
	v_lshl_add_u64 v[204:205], v[214:215], 0, s[56:57]
	s_mov_b32 m0, s34
	s_nop 0
	global_load_lds_dwordx4 v[204:205], off
	s_waitcnt vmcnt(8)
	s_waitcnt lgkmcnt(0)
	s_barrier
	s_waitcnt lgkmcnt(0)
	v_mfma_f32_16x16x32_bf16 v[110:113], v[130:133], v[162:165], v[110:113]
	v_mfma_f32_16x16x32_bf16 v[78:81], v[138:141], v[162:165], v[78:81]
	v_mfma_f32_16x16x32_bf16 v[106:109], v[130:133], v[170:173], v[106:109]
	v_mfma_f32_16x16x32_bf16 v[74:77], v[138:141], v[170:173], v[74:77]
	v_mfma_f32_16x16x32_bf16 v[102:105], v[130:133], v[188:191], v[102:105]
	v_mfma_f32_16x16x32_bf16 v[70:73], v[138:141], v[188:191], v[70:73]
	v_mfma_f32_16x16x32_bf16 v[98:101], v[130:133], v[196:199], v[98:101]
	v_mfma_f32_16x16x32_bf16 v[62:65], v[138:141], v[196:199], v[62:65]
	v_mfma_f32_16x16x32_bf16 v[110:113], v[134:137], v[166:169], v[110:113]
	v_mfma_f32_16x16x32_bf16 v[78:81], v[142:145], v[166:169], v[78:81]
	v_mfma_f32_16x16x32_bf16 v[106:109], v[134:137], v[184:187], v[106:109]
	v_mfma_f32_16x16x32_bf16 v[74:77], v[142:145], v[184:187], v[74:77]
	v_mfma_f32_16x16x32_bf16 v[102:105], v[134:137], v[192:195], v[102:105]
	v_mfma_f32_16x16x32_bf16 v[70:73], v[142:145], v[192:195], v[70:73]
	v_mfma_f32_16x16x32_bf16 v[98:101], v[134:137], v[200:203], v[98:101]
	v_mfma_f32_16x16x32_bf16 v[62:65], v[142:145], v[200:203], v[62:65]
	v_mfma_f32_16x16x32_bf16 v[46:49], v[146:149], v[162:165], v[46:49]
	v_mfma_f32_16x16x32_bf16 v[12:15], v[154:157], v[162:165], v[12:15]
	v_mfma_f32_16x16x32_bf16 v[38:41], v[146:149], v[170:173], v[38:41]
	v_mfma_f32_16x16x32_bf16 v[8:11], v[154:157], v[170:173], v[8:11]
	v_mfma_f32_16x16x32_bf16 v[34:37], v[146:149], v[188:191], v[34:37]
	v_mfma_f32_16x16x32_bf16 v[4:7], v[154:157], v[188:191], v[4:7]
	v_mfma_f32_16x16x32_bf16 v[26:29], v[146:149], v[196:199], v[26:29]
	v_mfma_f32_16x16x32_bf16 v[0:3], v[154:157], v[196:199], v[0:3]
	v_mfma_f32_16x16x32_bf16 v[46:49], v[150:153], v[166:169], v[46:49]
	v_mfma_f32_16x16x32_bf16 v[12:15], v[158:161], v[166:169], v[12:15]
	v_mfma_f32_16x16x32_bf16 v[38:41], v[150:153], v[184:187], v[38:41]
	v_mfma_f32_16x16x32_bf16 v[8:11], v[158:161], v[184:187], v[8:11]
	v_mfma_f32_16x16x32_bf16 v[34:37], v[150:153], v[192:195], v[34:37]
	v_mfma_f32_16x16x32_bf16 v[4:7], v[158:161], v[192:195], v[4:7]
	v_mfma_f32_16x16x32_bf16 v[26:29], v[150:153], v[200:203], v[26:29]
	v_mfma_f32_16x16x32_bf16 v[0:3], v[158:161], v[200:203], v[0:3]
	s_barrier
	s_add_i32 s42, s42, 2
	s_add_u32 s40, s40, 0x100
	s_addc_u32 s41, s41, 0
	s_cmpk_gt_u32 s42, 0x53
	s_mov_b64 s[10:11], s[12:13]
	s_cbranch_scc0 .LBB0_32
	s_setprio 0
	s_and_b64 vcc, exec, s[6:7]
	s_cbranch_vccz .LBB0_35
	s_barrier

.LBB0_67:
	s_ashr_i32 s21, s20, 31
	s_lshl_b64 s[10:11], s[20:21], 20
	s_add_u32 s22, s34, s10
	s_addc_u32 s23, s35, s11
	s_and_b64 s[10:11], s[4:5], exec
	s_cselect_b32 s21, s23, s7
	s_cselect_b32 s28, s22, s6
	s_ashr_i32 s19, s18, 31
	s_lshl_b64 s[10:11], s[18:19], 20
	s_add_u32 s24, s36, s10
	s_addc_u32 s25, s37, s11
	s_and_b64 s[10:11], s[4:5], exec
	s_cselect_b32 s19, s25, s9
	s_cselect_b32 s29, s24, s8
	s_add_u32 s6, s6, 0x80080
	s_addc_u32 s7, s7, 0
	s_add_u32 s30, s8, 0x100
	v_mov_b32_e32 v4, 0
	s_addc_u32 s31, s9, 0
	s_mov_b32 s51, -2
	v_mov_b32_e32 v5, v4
	v_mov_b32_e32 v6, v4
	v_mov_b32_e32 v7, v4
	v_mov_b32_e32 v0, v4
	v_mov_b32_e32 v1, v4
	v_mov_b32_e32 v2, v4
	v_mov_b32_e32 v3, v4
	v_mov_b32_e32 v26, v4
	v_mov_b32_e32 v27, v4
	v_mov_b32_e32 v28, v4
	v_mov_b32_e32 v29, v4
	v_mov_b32_e32 v34, v4
	v_mov_b32_e32 v35, v4
	v_mov_b32_e32 v36, v4
	v_mov_b32_e32 v37, v4
	v_mov_b32_e32 v42, v4
	v_mov_b32_e32 v43, v4
	v_mov_b32_e32 v44, v4
	v_mov_b32_e32 v45, v4
	v_mov_b32_e32 v50, v4
	v_mov_b32_e32 v51, v4
	v_mov_b32_e32 v52, v4
	v_mov_b32_e32 v53, v4
	v_mov_b32_e32 v90, v4
	v_mov_b32_e32 v91, v4
	v_mov_b32_e32 v92, v4
	v_mov_b32_e32 v93, v4
	v_mov_b32_e32 v94, v4
	v_mov_b32_e32 v95, v4
	v_mov_b32_e32 v96, v4
	v_mov_b32_e32 v97, v4
	v_mov_b32_e32 v12, v4
	v_mov_b32_e32 v13, v4
	v_mov_b32_e32 v14, v4
	v_mov_b32_e32 v15, v4
	v_mov_b32_e32 v8, v4
	v_mov_b32_e32 v9, v4
	v_mov_b32_e32 v10, v4
	v_mov_b32_e32 v11, v4
	v_mov_b32_e32 v18, v4
	v_mov_b32_e32 v19, v4
	v_mov_b32_e32 v20, v4
	v_mov_b32_e32 v21, v4
	v_mov_b32_e32 v22, v4
	v_mov_b32_e32 v23, v4
	v_mov_b32_e32 v24, v4
	v_mov_b32_e32 v25, v4
	v_mov_b32_e32 v30, v4
	v_mov_b32_e32 v31, v4
	v_mov_b32_e32 v32, v4
	v_mov_b32_e32 v33, v4
	v_mov_b32_e32 v38, v4
	v_mov_b32_e32 v39, v4
	v_mov_b32_e32 v40, v4
	v_mov_b32_e32 v41, v4
	v_mov_b32_e32 v46, v4
	v_mov_b32_e32 v47, v4
	v_mov_b32_e32 v48, v4
	v_mov_b32_e32 v49, v4
	s_waitcnt vmcnt(0)
	v_mov_b32_e32 v58, v4
	v_mov_b32_e32 v59, v4
	v_mov_b32_e32 v60, v4
	v_mov_b32_e32 v61, v4
	v_mov_b32_e32 v98, v4
	v_mov_b32_e32 v99, v4
	v_mov_b32_e32 v100, v4
	v_mov_b32_e32 v101, v4
	v_mov_b32_e32 v102, v4
	v_mov_b32_e32 v103, v4
	v_mov_b32_e32 v104, v4
	v_mov_b32_e32 v105, v4
	v_mov_b32_e32 v122, v4
	v_mov_b32_e32 v123, v4
	v_mov_b32_e32 v124, v4
	v_mov_b32_e32 v125, v4
	v_mov_b32_e32 v130, v4
	v_mov_b32_e32 v131, v4
	v_mov_b32_e32 v132, v4
	v_mov_b32_e32 v133, v4
	v_mov_b32_e32 v138, v4
	v_mov_b32_e32 v139, v4
	v_mov_b32_e32 v140, v4
	v_mov_b32_e32 v141, v4
	v_mov_b32_e32 v146, v4
	v_mov_b32_e32 v147, v4
	v_mov_b32_e32 v148, v4
	v_mov_b32_e32 v149, v4
	v_mov_b32_e32 v154, v4
	v_mov_b32_e32 v155, v4
	v_mov_b32_e32 v156, v4
	v_mov_b32_e32 v157, v4
	v_mov_b32_e32 v158, v4
	v_mov_b32_e32 v159, v4
	v_mov_b32_e32 v160, v4
	v_mov_b32_e32 v161, v4
	v_mov_b32_e32 v106, v4
	v_mov_b32_e32 v107, v4
	v_mov_b32_e32 v108, v4
	v_mov_b32_e32 v109, v4
	v_mov_b32_e32 v110, v4
	v_mov_b32_e32 v111, v4
	v_mov_b32_e32 v112, v4
	v_mov_b32_e32 v113, v4
	v_mov_b32_e32 v114, v4
	v_mov_b32_e32 v115, v4
	v_mov_b32_e32 v116, v4
	v_mov_b32_e32 v117, v4
	v_mov_b32_e32 v118, v4
	v_mov_b32_e32 v119, v4
	v_mov_b32_e32 v120, v4
	v_mov_b32_e32 v121, v4
	v_mov_b32_e32 v126, v4
	v_mov_b32_e32 v127, v4
	v_mov_b32_e32 v128, v4
	v_mov_b32_e32 v129, v4
	v_mov_b32_e32 v134, v4
	v_mov_b32_e32 v135, v4
	v_mov_b32_e32 v136, v4
	v_mov_b32_e32 v137, v4
	v_mov_b32_e32 v142, v4
	v_mov_b32_e32 v143, v4
	v_mov_b32_e32 v144, v4
	v_mov_b32_e32 v145, v4
	v_mov_b32_e32 v150, v4
	v_mov_b32_e32 v151, v4
	v_mov_b32_e32 v152, v4
	v_mov_b32_e32 v153, v4
	v_readlane_b32 s100, v253, 1
	s_cmp_ge_u32 s100, 4
	s_cbranch_scc1 .Lprio_0
	s_setprio 1
.Lprio_0:
.LBB0_68:
	s_add_u32 s8, s6, 0xfff80080
	s_addc_u32 s9, s7, -1
	s_add_i32 s33, 0, 0x10000
	s_cmp_eq_u32 s51, 28
	s_cselect_b32 s11, s21, s9
	s_cselect_b32 s10, s28, s8
	v_add_u32_e32 v16, s33, v190
	s_cselect_b32 s9, s19, s31
	s_cselect_b32 s8, s29, s30
	s_add_i32 s54, 0, 0x14000
	ds_read_b128 v[54:57], v16
	ds_read_b128 v[62:65], v16 offset:1024
	ds_read_b128 v[66:69], v16 offset:2048
	ds_read_b128 v[70:73], v16 offset:3072
	v_add_u32_e32 v16, s54, v190
	ds_read_b128 v[74:77], v16
	ds_read_b128 v[78:81], v16 offset:1024
	ds_read_b128 v[82:85], v16 offset:2048
	ds_read_b128 v[86:89], v16 offset:3072
	s_cmp_eq_u32 s51, -2
	s_cbranch_scc1 .Lup_skipA10
	v_lshl_add_u64 v[214:215], v[236:237], 0, s[56:57]
	s_mov_b32 m0, s46
	s_nop 0
	global_load_lds_dwordx4 v[214:215], off
	v_lshl_add_u64 v[214:215], v[238:239], 0, s[56:57]
	s_mov_b32 m0, s47
	s_nop 0
	global_load_lds_dwordx4 v[214:215], off
.Lup_skipA10:
	v_lshl_add_u64 v[214:215], s[6:7], 0, v[180:181]
	s_add_i32 m0, s41, 0xc000
	ds_read_b128 v[170:173], v192
	ds_read_b128 v[184:187], v192 offset:1024
	ds_read_b128 v[194:197], v192 offset:2048
	ds_read_b128 v[198:201], v192 offset:3072
	ds_read_b128 v[202:205], v192 offset:4096
	ds_read_b128 v[206:209], v192 offset:5120
	ds_read_b128 v[210:213], v192 offset:6144
	ds_read_b128 v[222:225], v192 offset:7168
	global_load_lds_dwordx4 v[214:215], off
	v_lshl_add_u64 v[214:215], s[6:7], 0, v[182:183]
	s_add_i32 m0, s41, 0xe000
	s_nop 0
	global_load_lds_dwordx4 v[214:215], off
	s_waitcnt vmcnt(8)
	s_waitcnt lgkmcnt(0)
	s_barrier
	s_waitcnt lgkmcnt(0)
	v_mfma_f32_16x16x32_bf16 v[150:153], v[54:57], v[170:173], v[150:153]
	v_mfma_f32_16x16x32_bf16 v[142:145], v[66:69], v[170:173], v[142:145]
	v_mfma_f32_16x16x32_bf16 v[134:137], v[54:57], v[194:197], v[134:137]
	v_mfma_f32_16x16x32_bf16 v[126:129], v[66:69], v[194:197], v[126:129]
	v_mfma_f32_16x16x32_bf16 v[118:121], v[54:57], v[202:205], v[118:121]
	v_mfma_f32_16x16x32_bf16 v[114:117], v[66:69], v[202:205], v[114:117]
	v_mfma_f32_16x16x32_bf16 v[110:113], v[54:57], v[210:213], v[110:113]
	v_mfma_f32_16x16x32_bf16 v[106:109], v[66:69], v[210:213], v[106:109]
	v_mfma_f32_16x16x32_bf16 v[150:153], v[62:65], v[184:187], v[150:153]
	v_mfma_f32_16x16x32_bf16 v[142:145], v[70:73], v[184:187], v[142:145]
	v_mfma_f32_16x16x32_bf16 v[134:137], v[62:65], v[198:201], v[134:137]
	v_mfma_f32_16x16x32_bf16 v[126:129], v[70:73], v[198:201], v[126:129]
	v_mfma_f32_16x16x32_bf16 v[118:121], v[62:65], v[206:209], v[118:121]
	v_mfma_f32_16x16x32_bf16 v[114:117], v[70:73], v[206:209], v[114:117]
	v_mfma_f32_16x16x32_bf16 v[110:113], v[62:65], v[222:225], v[110:113]
	v_mfma_f32_16x16x32_bf16 v[106:109], v[70:73], v[222:225], v[106:109]
	v_mfma_f32_16x16x32_bf16 v[158:161], v[74:77], v[170:173], v[158:161]
	v_mfma_f32_16x16x32_bf16 v[154:157], v[82:85], v[170:173], v[154:157]
	v_mfma_f32_16x16x32_bf16 v[146:149], v[74:77], v[194:197], v[146:149]
	v_mfma_f32_16x16x32_bf16 v[138:141], v[82:85], v[194:197], v[138:141]
	v_mfma_f32_16x16x32_bf16 v[130:133], v[74:77], v[202:205], v[130:133]
	v_mfma_f32_16x16x32_bf16 v[122:125], v[82:85], v[202:205], v[122:125]
	v_mfma_f32_16x16x32_bf16 v[102:105], v[74:77], v[210:213], v[102:105]
	v_mfma_f32_16x16x32_bf16 v[98:101], v[82:85], v[210:213], v[98:101]
	v_mfma_f32_16x16x32_bf16 v[158:161], v[78:81], v[184:187], v[158:161]
	v_mfma_f32_16x16x32_bf16 v[154:157], v[86:89], v[184:187], v[154:157]
	v_mfma_f32_16x16x32_bf16 v[146:149], v[78:81], v[198:201], v[146:149]
	v_mfma_f32_16x16x32_bf16 v[138:141], v[86:89], v[198:201], v[138:141]
	v_mfma_f32_16x16x32_bf16 v[130:133], v[78:81], v[206:209], v[130:133]
	v_mfma_f32_16x16x32_bf16 v[122:125], v[86:89], v[206:209], v[122:125]
	v_mfma_f32_16x16x32_bf16 v[102:105], v[78:81], v[222:225], v[102:105]
	v_mfma_f32_16x16x32_bf16 v[98:101], v[86:89], v[222:225], v[98:101]
	s_barrier
	s_add_i32 s33, s33, s38
	v_lshl_add_u64 v[214:215], s[8:9], 0, v[166:167]
	s_mov_b32 m0, s33
	ds_read_b128 v[170:173], v192 offset:16384
	ds_read_b128 v[184:187], v192 offset:17408
	ds_read_b128 v[194:197], v192 offset:18432
	ds_read_b128 v[198:201], v192 offset:19456
	ds_read_b128 v[202:205], v192 offset:20480
	ds_read_b128 v[206:209], v192 offset:21504
	ds_read_b128 v[210:213], v192 offset:22528
	ds_read_b128 v[222:225], v192 offset:23552
	global_load_lds_dwordx4 v[214:215], off
	s_add_i32 m0, s33, 0x2000
	s_add_u32 s52, s8, 0x80000
	v_lshl_add_u64 v[234:235], s[8:9], 0, v[162:163]
	s_addc_u32 s53, s9, 0
	s_add_i32 s33, s54, s38
	global_load_lds_dwordx4 v[234:235], off
	v_lshl_add_u64 v[230:231], s[52:53], 0, v[166:167]
	s_mov_b32 m0, s33
	v_lshl_add_u64 v[236:237], s[10:11], 0, v[168:169]
	global_load_lds_dwordx4 v[230:231], off
	v_lshl_add_u64 v[230:231], s[52:53], 0, v[162:163]
	s_add_i32 m0, s33, 0x2000
	v_lshl_add_u64 v[238:239], s[10:11], 0, v[164:165]
	global_load_lds_dwordx4 v[230:231], off
	s_waitcnt vmcnt(6)
	s_waitcnt lgkmcnt(0)
	s_barrier
	s_waitcnt lgkmcnt(0)
	v_mfma_f32_16x16x32_bf16 v[58:61], v[54:57], v[170:173], v[58:61]
	v_mfma_f32_16x16x32_bf16 v[46:49], v[66:69], v[170:173], v[46:49]
	v_mfma_f32_16x16x32_bf16 v[38:41], v[54:57], v[194:197], v[38:41]
	v_mfma_f32_16x16x32_bf16 v[30:33], v[66:69], v[194:197], v[30:33]
	v_mfma_f32_16x16x32_bf16 v[22:25], v[54:57], v[202:205], v[22:25]
	v_mfma_f32_16x16x32_bf16 v[18:21], v[66:69], v[202:205], v[18:21]
	v_mfma_f32_16x16x32_bf16 v[8:11], v[54:57], v[210:213], v[8:11]
	v_mfma_f32_16x16x32_bf16 v[12:15], v[66:69], v[210:213], v[12:15]
	v_mfma_f32_16x16x32_bf16 v[58:61], v[62:65], v[184:187], v[58:61]
	v_mfma_f32_16x16x32_bf16 v[46:49], v[70:73], v[184:187], v[46:49]
	v_mfma_f32_16x16x32_bf16 v[38:41], v[62:65], v[198:201], v[38:41]
	v_mfma_f32_16x16x32_bf16 v[30:33], v[70:73], v[198:201], v[30:33]
	v_mfma_f32_16x16x32_bf16 v[22:25], v[62:65], v[206:209], v[22:25]
	v_mfma_f32_16x16x32_bf16 v[18:21], v[70:73], v[206:209], v[18:21]
	v_mfma_f32_16x16x32_bf16 v[8:11], v[62:65], v[222:225], v[8:11]
	v_mfma_f32_16x16x32_bf16 v[12:15], v[70:73], v[222:225], v[12:15]
	v_mfma_f32_16x16x32_bf16 v[50:53], v[74:77], v[194:197], v[50:53]
	v_mfma_f32_16x16x32_bf16 v[42:45], v[82:85], v[194:197], v[42:45]
	v_mfma_f32_16x16x32_bf16 v[34:37], v[74:77], v[202:205], v[34:37]
	v_mfma_f32_16x16x32_bf16 v[26:29], v[82:85], v[202:205], v[26:29]
	v_mfma_f32_16x16x32_bf16 v[0:3], v[74:77], v[210:213], v[0:3]
	v_mfma_f32_16x16x32_bf16 v[4:7], v[82:85], v[210:213], v[4:7]
	v_mfma_f32_16x16x32_bf16 v[54:57], v[74:77], v[170:173], v[94:97]
	v_mfma_f32_16x16x32_bf16 v[62:65], v[82:85], v[170:173], v[90:93]
	v_mfma_f32_16x16x32_bf16 v[50:53], v[78:81], v[198:201], v[50:53]
	v_mfma_f32_16x16x32_bf16 v[42:45], v[86:89], v[198:201], v[42:45]
	v_mfma_f32_16x16x32_bf16 v[34:37], v[78:81], v[206:209], v[34:37]
	v_mfma_f32_16x16x32_bf16 v[26:29], v[86:89], v[206:209], v[26:29]
	v_mfma_f32_16x16x32_bf16 v[0:3], v[78:81], v[222:225], v[0:3]
	v_mfma_f32_16x16x32_bf16 v[4:7], v[86:89], v[222:225], v[4:7]
	v_mfma_f32_16x16x32_bf16 v[54:57], v[78:81], v[184:187], v[54:57]
	v_mfma_f32_16x16x32_bf16 v[62:65], v[86:89], v[184:187], v[62:65]
	s_barrier
	s_add_i32 s33, 0, 0x18000
	v_add_u32_e32 v16, s33, v190
	s_add_i32 s52, 0, 0x1c000
	ds_read_b128 v[66:69], v16
	ds_read_b128 v[70:73], v16 offset:1024
	ds_read_b128 v[74:77], v16 offset:2048
	ds_read_b128 v[78:81], v16 offset:3072
	v_add_u32_e32 v16, s52, v190
	ds_read_b128 v[82:85], v16
	ds_read_b128 v[86:89], v16 offset:1024
	ds_read_b128 v[170:173], v16 offset:2048
	ds_read_b128 v[184:187], v16 offset:3072
	s_mov_b32 m0, s41
	s_nop 0
	global_load_lds_dwordx4 v[236:237], off
	s_mov_b32 m0, s42
	s_nop 0
	global_load_lds_dwordx4 v[238:239], off
	s_add_u32 s10, s10, 0x80000
	s_addc_u32 s11, s11, 0
	s_mov_b32 m0, s43
	v_lshl_add_u64 v[230:231], s[10:11], 0, v[168:169]
	ds_read_b128 v[90:93], v192 offset:32768
	ds_read_b128 v[94:97], v192 offset:33792
	ds_read_b128 v[194:197], v192 offset:34816
	ds_read_b128 v[198:201], v192 offset:35840
	ds_read_b128 v[202:205], v192 offset:36864
	ds_read_b128 v[206:209], v192 offset:37888
	ds_read_b128 v[210:213], v192 offset:38912
	ds_read_b128 v[222:225], v192 offset:39936
	global_load_lds_dwordx4 v[230:231], off
	v_lshl_add_u64 v[230:231], s[10:11], 0, v[164:165]
	s_mov_b32 m0, s44
	s_nop 0
	global_load_lds_dwordx4 v[230:231], off
	s_waitcnt vmcnt(8)
	s_waitcnt lgkmcnt(0)
	s_barrier
	s_waitcnt lgkmcnt(0)
	v_mfma_f32_16x16x32_bf16 v[150:153], v[66:69], v[90:93], v[150:153]
	v_mfma_f32_16x16x32_bf16 v[142:145], v[74:77], v[90:93], v[142:145]
	v_mfma_f32_16x16x32_bf16 v[134:137], v[66:69], v[194:197], v[134:137]
	v_mfma_f32_16x16x32_bf16 v[126:129], v[74:77], v[194:197], v[126:129]
	v_mfma_f32_16x16x32_bf16 v[118:121], v[66:69], v[202:205], v[118:121]
	v_mfma_f32_16x16x32_bf16 v[114:117], v[74:77], v[202:205], v[114:117]
	v_mfma_f32_16x16x32_bf16 v[110:113], v[66:69], v[210:213], v[110:113]
	v_mfma_f32_16x16x32_bf16 v[106:109], v[74:77], v[210:213], v[106:109]
	v_mfma_f32_16x16x32_bf16 v[150:153], v[70:73], v[94:97], v[150:153]
	v_mfma_f32_16x16x32_bf16 v[142:145], v[78:81], v[94:97], v[142:145]
	v_mfma_f32_16x16x32_bf16 v[134:137], v[70:73], v[198:201], v[134:137]
	v_mfma_f32_16x16x32_bf16 v[126:129], v[78:81], v[198:201], v[126:129]
	v_mfma_f32_16x16x32_bf16 v[118:121], v[70:73], v[206:209], v[118:121]
	v_mfma_f32_16x16x32_bf16 v[114:117], v[78:81], v[206:209], v[114:117]
	v_mfma_f32_16x16x32_bf16 v[110:113], v[70:73], v[222:225], v[110:113]
	v_mfma_f32_16x16x32_bf16 v[106:109], v[78:81], v[222:225], v[106:109]
	v_mfma_f32_16x16x32_bf16 v[158:161], v[82:85], v[90:93], v[158:161]
	v_mfma_f32_16x16x32_bf16 v[90:93], v[170:173], v[90:93], v[154:157]
	v_mfma_f32_16x16x32_bf16 v[154:157], v[184:187], v[94:97], v[90:93]
	v_mfma_f32_16x16x32_bf16 v[90:93], v[82:85], v[194:197], v[146:149]
	v_mfma_f32_16x16x32_bf16 v[146:149], v[86:89], v[198:201], v[90:93]
	v_mfma_f32_16x16x32_bf16 v[90:93], v[170:173], v[194:197], v[138:141]
	v_mfma_f32_16x16x32_bf16 v[138:141], v[184:187], v[198:201], v[90:93]
	v_mfma_f32_16x16x32_bf16 v[90:93], v[82:85], v[202:205], v[130:133]
	v_mfma_f32_16x16x32_bf16 v[130:133], v[86:89], v[206:209], v[90:93]
	v_mfma_f32_16x16x32_bf16 v[90:93], v[170:173], v[202:205], v[122:125]
	v_mfma_f32_16x16x32_bf16 v[122:125], v[184:187], v[206:209], v[90:93]
	v_mfma_f32_16x16x32_bf16 v[90:93], v[82:85], v[210:213], v[102:105]
	v_mfma_f32_16x16x32_bf16 v[102:105], v[86:89], v[222:225], v[90:93]
	v_mfma_f32_16x16x32_bf16 v[90:93], v[170:173], v[210:213], v[98:101]
	v_mfma_f32_16x16x32_bf16 v[158:161], v[86:89], v[94:97], v[158:161]
	v_mfma_f32_16x16x32_bf16 v[98:101], v[184:187], v[222:225], v[90:93]
	s_barrier
	s_add_i32 s10, s33, s38
	v_lshl_add_u64 v[94:95], v[214:215], 0, s[56:57]
	s_mov_b32 m0, s10
	s_nop 0
	ds_read_b128 v[90:93], v192 offset:49152
	ds_read_b128 v[194:197], v192 offset:50176
	ds_read_b128 v[198:201], v192 offset:51200
	ds_read_b128 v[202:205], v192 offset:52224
	ds_read_b128 v[206:209], v192 offset:53248
	ds_read_b128 v[210:213], v192 offset:54272
	ds_read_b128 v[222:225], v192 offset:55296
	ds_read_b128 v[230:233], v192 offset:56320
	global_load_lds_dwordx4 v[94:95], off
	s_add_i32 m0, s10, 0x2000
	s_add_u32 s8, s8, 0x80080
	v_lshl_add_u64 v[94:95], v[234:235], 0, s[56:57]
	s_addc_u32 s9, s9, 0
	s_add_i32 s10, s52, s38
	global_load_lds_dwordx4 v[94:95], off
	v_lshl_add_u64 v[94:95], s[8:9], 0, v[166:167]
	s_mov_b32 m0, s10
	s_nop 0
	global_load_lds_dwordx4 v[94:95], off
	v_lshl_add_u64 v[94:95], s[8:9], 0, v[162:163]
	s_add_i32 m0, s10, 0x2000
	s_nop 0
	global_load_lds_dwordx4 v[94:95], off
	s_cmp_eq_u32 s51, 28
	s_cbranch_scc0 .Lup_notlast
	v_lshl_add_u64 v[94:95], v[236:237], 0, s[56:57]
	s_mov_b32 m0, s46
	s_nop 0
	global_load_lds_dwordx4 v[94:95], off
	v_lshl_add_u64 v[94:95], v[238:239], 0, s[56:57]
	s_mov_b32 m0, s47
	s_nop 0
	global_load_lds_dwordx4 v[94:95], off
	s_waitcnt vmcnt(8)
	s_branch .Lup_join

.Lup_join:
	s_waitcnt lgkmcnt(0)
	s_barrier
	s_waitcnt lgkmcnt(0)
	v_mfma_f32_16x16x32_bf16 v[58:61], v[66:69], v[90:93], v[58:61]
	v_mfma_f32_16x16x32_bf16 v[46:49], v[74:77], v[90:93], v[46:49]
	v_mfma_f32_16x16x32_bf16 v[38:41], v[66:69], v[198:201], v[38:41]
	v_mfma_f32_16x16x32_bf16 v[30:33], v[74:77], v[198:201], v[30:33]
	v_mfma_f32_16x16x32_bf16 v[22:25], v[66:69], v[206:209], v[22:25]
	v_mfma_f32_16x16x32_bf16 v[18:21], v[74:77], v[206:209], v[18:21]
	v_mfma_f32_16x16x32_bf16 v[8:11], v[66:69], v[222:225], v[8:11]
	v_mfma_f32_16x16x32_bf16 v[12:15], v[74:77], v[222:225], v[12:15]
	v_mfma_f32_16x16x32_bf16 v[58:61], v[70:73], v[194:197], v[58:61]
	v_mfma_f32_16x16x32_bf16 v[46:49], v[78:81], v[194:197], v[46:49]
	v_mfma_f32_16x16x32_bf16 v[38:41], v[70:73], v[202:205], v[38:41]
	v_mfma_f32_16x16x32_bf16 v[30:33], v[78:81], v[202:205], v[30:33]
	v_mfma_f32_16x16x32_bf16 v[22:25], v[70:73], v[210:213], v[22:25]
	v_mfma_f32_16x16x32_bf16 v[18:21], v[78:81], v[210:213], v[18:21]
	v_mfma_f32_16x16x32_bf16 v[8:11], v[70:73], v[230:233], v[8:11]
	v_mfma_f32_16x16x32_bf16 v[12:15], v[78:81], v[230:233], v[12:15]
	v_mfma_f32_16x16x32_bf16 v[54:57], v[82:85], v[90:93], v[54:57]
	v_mfma_f32_16x16x32_bf16 v[94:97], v[86:89], v[194:197], v[54:57]
	v_mfma_f32_16x16x32_bf16 v[54:57], v[170:173], v[90:93], v[62:65]
	v_mfma_f32_16x16x32_bf16 v[50:53], v[82:85], v[198:201], v[50:53]
	v_mfma_f32_16x16x32_bf16 v[42:45], v[170:173], v[198:201], v[42:45]
	v_mfma_f32_16x16x32_bf16 v[34:37], v[82:85], v[206:209], v[34:37]
	v_mfma_f32_16x16x32_bf16 v[26:29], v[170:173], v[206:209], v[26:29]
	v_mfma_f32_16x16x32_bf16 v[0:3], v[82:85], v[222:225], v[0:3]
	v_mfma_f32_16x16x32_bf16 v[4:7], v[170:173], v[222:225], v[4:7]
	v_mfma_f32_16x16x32_bf16 v[90:93], v[184:187], v[194:197], v[54:57]
	v_mfma_f32_16x16x32_bf16 v[50:53], v[86:89], v[202:205], v[50:53]
	v_mfma_f32_16x16x32_bf16 v[42:45], v[184:187], v[202:205], v[42:45]
	v_mfma_f32_16x16x32_bf16 v[34:37], v[86:89], v[210:213], v[34:37]
	v_mfma_f32_16x16x32_bf16 v[26:29], v[184:187], v[210:213], v[26:29]
	v_mfma_f32_16x16x32_bf16 v[0:3], v[86:89], v[230:233], v[0:3]
	v_mfma_f32_16x16x32_bf16 v[4:7], v[184:187], v[230:233], v[4:7]
	s_barrier
	s_add_i32 s51, s51, 2
	s_add_u32 s6, s6, 0x100
	s_addc_u32 s7, s7, 0
	s_add_u32 s30, s30, 0x100
	s_addc_u32 s31, s31, 0
	s_cmp_gt_u32 s51, 29
	s_cbranch_scc0 .LBB0_68
	s_setprio 0
	s_and_b64 vcc, exec, s[16:17]
	s_cbranch_vccz .LBB0_71
	s_barrier

.LBB0_107:
	s_ashr_i32 s9, s8, 31
	s_lshl_b64 s[10:11], s[8:9], 20
	s_add_u32 s10, s20, s10
	s_addc_u32 s11, s21, s11
	s_and_b64 s[12:13], s[4:5], exec
	s_cselect_b32 s9, s11, s15
	s_cselect_b32 s40, s10, s14
	s_ashr_i32 s7, s6, 31
	s_lshl_b64 s[12:13], s[6:7], 20
	s_add_u32 s12, s22, s12
	s_addc_u32 s13, s23, s13
	s_and_b64 s[18:19], s[4:5], exec
	s_cselect_b32 s7, s13, s17
	s_cselect_b32 s41, s12, s16
	s_add_u32 s14, s14, 0x80080
	s_addc_u32 s15, s15, 0
	s_add_u32 s42, s16, 0x100
	v_mov_b32_e32 v0, 0
	s_addc_u32 s43, s17, 0
	s_mov_b32 s44, -2
	v_mov_b32_e32 v1, v0
	v_mov_b32_e32 v2, v0
	v_mov_b32_e32 v3, v0
	v_mov_b32_e32 v26, v0
	v_mov_b32_e32 v27, v0
	v_mov_b32_e32 v28, v0
	v_mov_b32_e32 v29, v0
	v_mov_b32_e32 v4, v0
	v_mov_b32_e32 v5, v0
	v_mov_b32_e32 v6, v0
	v_mov_b32_e32 v7, v0
	v_mov_b32_e32 v34, v0
	v_mov_b32_e32 v35, v0
	v_mov_b32_e32 v36, v0
	v_mov_b32_e32 v37, v0
	v_mov_b32_e32 v8, v0
	v_mov_b32_e32 v9, v0
	v_mov_b32_e32 v10, v0
	v_mov_b32_e32 v11, v0
	v_mov_b32_e32 v38, v0
	v_mov_b32_e32 v39, v0
	v_mov_b32_e32 v40, v0
	v_mov_b32_e32 v41, v0
	v_mov_b32_e32 v12, v0
	v_mov_b32_e32 v13, v0
	v_mov_b32_e32 v14, v0
	v_mov_b32_e32 v15, v0
	v_mov_b32_e32 v46, v0
	v_mov_b32_e32 v47, v0
	v_mov_b32_e32 v48, v0
	v_mov_b32_e32 v49, v0
	v_mov_b32_e32 v62, v0
	v_mov_b32_e32 v63, v0
	v_mov_b32_e32 v64, v0
	v_mov_b32_e32 v65, v0
	v_mov_b32_e32 v98, v0
	v_mov_b32_e32 v99, v0
	v_mov_b32_e32 v100, v0
	v_mov_b32_e32 v101, v0
	s_waitcnt vmcnt(0)
	v_mov_b32_e32 v70, v0
	v_mov_b32_e32 v71, v0
	v_mov_b32_e32 v72, v0
	v_mov_b32_e32 v73, v0
	v_mov_b32_e32 v102, v0
	v_mov_b32_e32 v103, v0
	v_mov_b32_e32 v104, v0
	v_mov_b32_e32 v105, v0
	v_mov_b32_e32 v74, v0
	v_mov_b32_e32 v75, v0
	v_mov_b32_e32 v76, v0
	v_mov_b32_e32 v77, v0
	v_mov_b32_e32 v106, v0
	v_mov_b32_e32 v107, v0
	v_mov_b32_e32 v108, v0
	v_mov_b32_e32 v109, v0
	v_mov_b32_e32 v78, v0
	v_mov_b32_e32 v79, v0
	v_mov_b32_e32 v80, v0
	v_mov_b32_e32 v81, v0
	v_mov_b32_e32 v110, v0
	v_mov_b32_e32 v111, v0
	v_mov_b32_e32 v112, v0
	v_mov_b32_e32 v113, v0
	v_mov_b32_e32 v18, v0
	v_mov_b32_e32 v19, v0
	v_mov_b32_e32 v20, v0
	v_mov_b32_e32 v21, v0
	v_mov_b32_e32 v50, v0
	v_mov_b32_e32 v51, v0
	v_mov_b32_e32 v52, v0
	v_mov_b32_e32 v53, v0
	v_mov_b32_e32 v22, v0
	v_mov_b32_e32 v23, v0
	v_mov_b32_e32 v24, v0
	v_mov_b32_e32 v25, v0
	v_mov_b32_e32 v54, v0
	v_mov_b32_e32 v55, v0
	v_mov_b32_e32 v56, v0
	v_mov_b32_e32 v57, v0
	v_mov_b32_e32 v30, v0
	v_mov_b32_e32 v31, v0
	v_mov_b32_e32 v32, v0
	v_mov_b32_e32 v33, v0
	v_mov_b32_e32 v58, v0
	v_mov_b32_e32 v59, v0
	v_mov_b32_e32 v60, v0
	v_mov_b32_e32 v61, v0
	v_mov_b32_e32 v42, v0
	v_mov_b32_e32 v43, v0
	v_mov_b32_e32 v44, v0
	v_mov_b32_e32 v45, v0
	v_mov_b32_e32 v66, v0
	v_mov_b32_e32 v67, v0
	v_mov_b32_e32 v68, v0
	v_mov_b32_e32 v69, v0
	v_mov_b32_e32 v82, v0
	v_mov_b32_e32 v83, v0
	v_mov_b32_e32 v84, v0
	v_mov_b32_e32 v85, v0
	v_mov_b32_e32 v114, v0
	v_mov_b32_e32 v115, v0
	v_mov_b32_e32 v116, v0
	v_mov_b32_e32 v117, v0
	v_mov_b32_e32 v86, v0
	v_mov_b32_e32 v87, v0
	v_mov_b32_e32 v88, v0
	v_mov_b32_e32 v89, v0
	v_mov_b32_e32 v118, v0
	v_mov_b32_e32 v119, v0
	v_mov_b32_e32 v120, v0
	v_mov_b32_e32 v121, v0
	v_mov_b32_e32 v90, v0
	v_mov_b32_e32 v91, v0
	v_mov_b32_e32 v92, v0
	v_mov_b32_e32 v93, v0
	v_mov_b32_e32 v122, v0
	v_mov_b32_e32 v123, v0
	v_mov_b32_e32 v124, v0
	v_mov_b32_e32 v125, v0
	v_mov_b32_e32 v94, v0
	v_mov_b32_e32 v95, v0
	v_mov_b32_e32 v96, v0
	v_mov_b32_e32 v97, v0
	v_mov_b32_e32 v126, v0
	v_mov_b32_e32 v127, v0
	v_mov_b32_e32 v128, v0
	v_mov_b32_e32 v129, v0
	v_readlane_b32 s100, v253, 1
	s_cmp_ge_u32 s100, 4
	s_cbranch_scc1 .Lprio_2
	s_setprio 1
.Lprio_2:
.LBB0_108:
	s_add_u32 s16, s14, 0xfff80080
	s_addc_u32 s17, s15, -1
	s_add_i32 s33, 0, 0x10000
	s_cmp_eq_u32 s44, 28
	s_cselect_b32 s19, s9, s17
	s_cselect_b32 s18, s40, s16
	s_cselect_b32 s17, s7, s43
	s_cselect_b32 s16, s41, s42
	s_add_i32 s45, 0, 0x14000
	v_add_u32_e32 v142, s33, v207
	v_add_u32_e32 v158, s45, v207
	ds_read_b128 v[130:133], v142
	ds_read_b128 v[134:137], v142 offset:1024
	ds_read_b128 v[138:141], v142 offset:2048
	ds_read_b128 v[142:145], v142 offset:3072
	ds_read_b128 v[146:149], v158
	ds_read_b128 v[150:153], v158 offset:1024
	ds_read_b128 v[154:157], v158 offset:2048
	ds_read_b128 v[158:161], v158 offset:3072
	v_lshl_add_u64 v[170:171], s[14:15], 0, v[180:181]
	s_add_i32 m0, s25, 0xc000
	ds_read_b128 v[162:165], v208
	ds_read_b128 v[166:169], v208 offset:1024
	ds_read_b128 v[184:187], v208 offset:2048
	ds_read_b128 v[188:191], v208 offset:3072
	ds_read_b128 v[192:195], v208 offset:4096
	ds_read_b128 v[196:199], v208 offset:5120
	ds_read_b128 v[200:203], v208 offset:6144
	ds_read_b128 v[210:213], v208 offset:7168
	global_load_lds_dwordx4 v[170:171], off
	v_lshl_add_u64 v[170:171], s[14:15], 0, v[182:183]
	s_add_i32 m0, s25, 0xe000
	s_nop 0
	global_load_lds_dwordx4 v[170:171], off
	s_waitcnt vmcnt(8)
	s_waitcnt lgkmcnt(0)
	s_barrier
	s_waitcnt lgkmcnt(0)
	v_mfma_f32_16x16x32_bf16 v[126:129], v[130:133], v[162:165], v[126:129]
	v_mfma_f32_16x16x32_bf16 v[94:97], v[138:141], v[162:165], v[94:97]
	v_mfma_f32_16x16x32_bf16 v[122:125], v[130:133], v[184:187], v[122:125]
	v_mfma_f32_16x16x32_bf16 v[90:93], v[138:141], v[184:187], v[90:93]
	v_mfma_f32_16x16x32_bf16 v[118:121], v[130:133], v[192:195], v[118:121]
	v_mfma_f32_16x16x32_bf16 v[86:89], v[138:141], v[192:195], v[86:89]
	v_mfma_f32_16x16x32_bf16 v[114:117], v[130:133], v[200:203], v[114:117]
	v_mfma_f32_16x16x32_bf16 v[82:85], v[138:141], v[200:203], v[82:85]
	v_mfma_f32_16x16x32_bf16 v[126:129], v[134:137], v[166:169], v[126:129]
	v_mfma_f32_16x16x32_bf16 v[94:97], v[142:145], v[166:169], v[94:97]
	v_mfma_f32_16x16x32_bf16 v[122:125], v[134:137], v[188:191], v[122:125]
	v_mfma_f32_16x16x32_bf16 v[90:93], v[142:145], v[188:191], v[90:93]
	v_mfma_f32_16x16x32_bf16 v[118:121], v[134:137], v[196:199], v[118:121]
	v_mfma_f32_16x16x32_bf16 v[86:89], v[142:145], v[196:199], v[86:89]
	v_mfma_f32_16x16x32_bf16 v[114:117], v[134:137], v[210:213], v[114:117]
	v_mfma_f32_16x16x32_bf16 v[82:85], v[142:145], v[210:213], v[82:85]
	v_mfma_f32_16x16x32_bf16 v[66:69], v[146:149], v[162:165], v[66:69]
	v_mfma_f32_16x16x32_bf16 v[42:45], v[154:157], v[162:165], v[42:45]
	v_mfma_f32_16x16x32_bf16 v[58:61], v[146:149], v[184:187], v[58:61]
	v_mfma_f32_16x16x32_bf16 v[30:33], v[154:157], v[184:187], v[30:33]
	v_mfma_f32_16x16x32_bf16 v[54:57], v[146:149], v[192:195], v[54:57]
	v_mfma_f32_16x16x32_bf16 v[22:25], v[154:157], v[192:195], v[22:25]
	v_mfma_f32_16x16x32_bf16 v[50:53], v[146:149], v[200:203], v[50:53]
	v_mfma_f32_16x16x32_bf16 v[18:21], v[154:157], v[200:203], v[18:21]
	v_mfma_f32_16x16x32_bf16 v[66:69], v[150:153], v[166:169], v[66:69]
	v_mfma_f32_16x16x32_bf16 v[42:45], v[158:161], v[166:169], v[42:45]
	v_mfma_f32_16x16x32_bf16 v[58:61], v[150:153], v[188:191], v[58:61]
	v_mfma_f32_16x16x32_bf16 v[30:33], v[158:161], v[188:191], v[30:33]
	v_mfma_f32_16x16x32_bf16 v[54:57], v[150:153], v[196:199], v[54:57]
	v_mfma_f32_16x16x32_bf16 v[22:25], v[158:161], v[196:199], v[22:25]
	v_mfma_f32_16x16x32_bf16 v[50:53], v[150:153], v[210:213], v[50:53]
	v_mfma_f32_16x16x32_bf16 v[18:21], v[158:161], v[210:213], v[18:21]
	s_barrier
	s_add_i32 s33, s33, s24
	v_lshl_add_u64 v[170:171], s[16:17], 0, v[178:179]
	s_mov_b32 m0, s33
	ds_read_b128 v[162:165], v208 offset:16384
	ds_read_b128 v[166:169], v208 offset:17408
	ds_read_b128 v[184:187], v208 offset:18432
	ds_read_b128 v[188:191], v208 offset:19456
	ds_read_b128 v[192:195], v208 offset:20480
	ds_read_b128 v[196:199], v208 offset:21504
	ds_read_b128 v[200:203], v208 offset:22528
	ds_read_b128 v[210:213], v208 offset:23552
	global_load_lds_dwordx4 v[170:171], off
	s_add_i32 m0, s33, 0x2000
	s_add_u32 s46, s16, 0x80000
	v_lshl_add_u64 v[172:173], s[16:17], 0, v[176:177]
	s_addc_u32 s47, s17, 0
	s_add_i32 s33, s45, s24
	global_load_lds_dwordx4 v[172:173], off
	v_lshl_add_u64 v[204:205], s[46:47], 0, v[178:179]
	s_mov_b32 m0, s33
	v_lshl_add_u64 v[214:215], s[18:19], 0, v[176:177]
	global_load_lds_dwordx4 v[204:205], off
	v_lshl_add_u64 v[204:205], s[46:47], 0, v[176:177]
	s_add_i32 m0, s33, 0x2000
	s_nop 0
	global_load_lds_dwordx4 v[204:205], off
	v_lshl_add_u64 v[204:205], s[18:19], 0, v[178:179]
	s_mov_b32 m0, s25
	s_nop 0
	global_load_lds_dwordx4 v[204:205], off
	s_mov_b32 m0, s26
	s_nop 0
	global_load_lds_dwordx4 v[214:215], off
	s_waitcnt vmcnt(8)
	s_waitcnt lgkmcnt(0)
	s_barrier
	s_waitcnt lgkmcnt(0)
	v_mfma_f32_16x16x32_bf16 v[110:113], v[130:133], v[162:165], v[110:113]
	v_mfma_f32_16x16x32_bf16 v[78:81], v[138:141], v[162:165], v[78:81]
	v_mfma_f32_16x16x32_bf16 v[106:109], v[130:133], v[184:187], v[106:109]
	v_mfma_f32_16x16x32_bf16 v[74:77], v[138:141], v[184:187], v[74:77]
	v_mfma_f32_16x16x32_bf16 v[102:105], v[130:133], v[192:195], v[102:105]
	v_mfma_f32_16x16x32_bf16 v[70:73], v[138:141], v[192:195], v[70:73]
	v_mfma_f32_16x16x32_bf16 v[98:101], v[130:133], v[200:203], v[98:101]
	v_mfma_f32_16x16x32_bf16 v[62:65], v[138:141], v[200:203], v[62:65]
	v_mfma_f32_16x16x32_bf16 v[110:113], v[134:137], v[166:169], v[110:113]
	v_mfma_f32_16x16x32_bf16 v[78:81], v[142:145], v[166:169], v[78:81]
	v_mfma_f32_16x16x32_bf16 v[106:109], v[134:137], v[188:191], v[106:109]
	v_mfma_f32_16x16x32_bf16 v[74:77], v[142:145], v[188:191], v[74:77]
	v_mfma_f32_16x16x32_bf16 v[102:105], v[134:137], v[196:199], v[102:105]
	v_mfma_f32_16x16x32_bf16 v[70:73], v[142:145], v[196:199], v[70:73]
	v_mfma_f32_16x16x32_bf16 v[98:101], v[134:137], v[210:213], v[98:101]
	v_mfma_f32_16x16x32_bf16 v[62:65], v[142:145], v[210:213], v[62:65]
	v_mfma_f32_16x16x32_bf16 v[46:49], v[146:149], v[162:165], v[46:49]
	v_mfma_f32_16x16x32_bf16 v[12:15], v[154:157], v[162:165], v[12:15]
	v_mfma_f32_16x16x32_bf16 v[38:41], v[146:149], v[184:187], v[38:41]
	v_mfma_f32_16x16x32_bf16 v[8:11], v[154:157], v[184:187], v[8:11]
	v_mfma_f32_16x16x32_bf16 v[34:37], v[146:149], v[192:195], v[34:37]
	v_mfma_f32_16x16x32_bf16 v[4:7], v[154:157], v[192:195], v[4:7]
	v_mfma_f32_16x16x32_bf16 v[26:29], v[146:149], v[200:203], v[26:29]
	v_mfma_f32_16x16x32_bf16 v[0:3], v[154:157], v[200:203], v[0:3]
	v_mfma_f32_16x16x32_bf16 v[46:49], v[150:153], v[166:169], v[46:49]
	v_mfma_f32_16x16x32_bf16 v[12:15], v[158:161], v[166:169], v[12:15]
	v_mfma_f32_16x16x32_bf16 v[38:41], v[150:153], v[188:191], v[38:41]
	v_mfma_f32_16x16x32_bf16 v[8:11], v[158:161], v[188:191], v[8:11]
	v_mfma_f32_16x16x32_bf16 v[34:37], v[150:153], v[196:199], v[34:37]
	v_mfma_f32_16x16x32_bf16 v[4:7], v[158:161], v[196:199], v[4:7]
	v_mfma_f32_16x16x32_bf16 v[26:29], v[150:153], v[210:213], v[26:29]
	v_mfma_f32_16x16x32_bf16 v[0:3], v[158:161], v[210:213], v[0:3]
	s_barrier
	s_add_i32 s33, 0, 0x18000
	s_add_i32 s45, 0, 0x1c000
	v_add_u32_e32 v142, s33, v207
	v_add_u32_e32 v158, s45, v207
	ds_read_b128 v[130:133], v142
	ds_read_b128 v[134:137], v142 offset:1024
	ds_read_b128 v[138:141], v142 offset:2048
	ds_read_b128 v[142:145], v142 offset:3072
	ds_read_b128 v[146:149], v158
	ds_read_b128 v[150:153], v158 offset:1024
	ds_read_b128 v[154:157], v158 offset:2048
	ds_read_b128 v[158:161], v158 offset:3072
	s_add_u32 s18, s18, 0x80000
	s_addc_u32 s19, s19, 0
	s_mov_b32 m0, s27
	v_lshl_add_u64 v[222:223], s[18:19], 0, v[178:179]
	ds_read_b128 v[162:165], v208 offset:32768
	ds_read_b128 v[166:169], v208 offset:33792
	ds_read_b128 v[184:187], v208 offset:34816
	ds_read_b128 v[188:191], v208 offset:35840
	ds_read_b128 v[192:195], v208 offset:36864
	ds_read_b128 v[196:199], v208 offset:37888
	ds_read_b128 v[200:203], v208 offset:38912
	ds_read_b128 v[210:213], v208 offset:39936
	global_load_lds_dwordx4 v[222:223], off
	v_lshl_add_u64 v[222:223], s[18:19], 0, v[176:177]
	s_mov_b32 m0, s28
	s_nop 0
	global_load_lds_dwordx4 v[222:223], off
	s_waitcnt vmcnt(8)
	s_waitcnt lgkmcnt(0)
	s_barrier
	s_waitcnt lgkmcnt(0)
	v_mfma_f32_16x16x32_bf16 v[126:129], v[130:133], v[162:165], v[126:129]
	v_mfma_f32_16x16x32_bf16 v[94:97], v[138:141], v[162:165], v[94:97]
	v_mfma_f32_16x16x32_bf16 v[122:125], v[130:133], v[184:187], v[122:125]
	v_mfma_f32_16x16x32_bf16 v[90:93], v[138:141], v[184:187], v[90:93]
	v_mfma_f32_16x16x32_bf16 v[118:121], v[130:133], v[192:195], v[118:121]
	v_mfma_f32_16x16x32_bf16 v[86:89], v[138:141], v[192:195], v[86:89]
	v_mfma_f32_16x16x32_bf16 v[114:117], v[130:133], v[200:203], v[114:117]
	v_mfma_f32_16x16x32_bf16 v[82:85], v[138:141], v[200:203], v[82:85]
	v_mfma_f32_16x16x32_bf16 v[126:129], v[134:137], v[166:169], v[126:129]
	v_mfma_f32_16x16x32_bf16 v[94:97], v[142:145], v[166:169], v[94:97]
	v_mfma_f32_16x16x32_bf16 v[122:125], v[134:137], v[188:191], v[122:125]
	v_mfma_f32_16x16x32_bf16 v[90:93], v[142:145], v[188:191], v[90:93]
	v_mfma_f32_16x16x32_bf16 v[118:121], v[134:137], v[196:199], v[118:121]
	v_mfma_f32_16x16x32_bf16 v[86:89], v[142:145], v[196:199], v[86:89]
	v_mfma_f32_16x16x32_bf16 v[114:117], v[134:137], v[210:213], v[114:117]
	v_mfma_f32_16x16x32_bf16 v[82:85], v[142:145], v[210:213], v[82:85]
	v_mfma_f32_16x16x32_bf16 v[66:69], v[146:149], v[162:165], v[66:69]
	v_mfma_f32_16x16x32_bf16 v[42:45], v[154:157], v[162:165], v[42:45]
	v_mfma_f32_16x16x32_bf16 v[58:61], v[146:149], v[184:187], v[58:61]
	v_mfma_f32_16x16x32_bf16 v[30:33], v[154:157], v[184:187], v[30:33]
	v_mfma_f32_16x16x32_bf16 v[54:57], v[146:149], v[192:195], v[54:57]
	v_mfma_f32_16x16x32_bf16 v[22:25], v[154:157], v[192:195], v[22:25]
	v_mfma_f32_16x16x32_bf16 v[50:53], v[146:149], v[200:203], v[50:53]
	v_mfma_f32_16x16x32_bf16 v[18:21], v[154:157], v[200:203], v[18:21]
	v_mfma_f32_16x16x32_bf16 v[66:69], v[150:153], v[166:169], v[66:69]
	v_mfma_f32_16x16x32_bf16 v[42:45], v[158:161], v[166:169], v[42:45]
	v_mfma_f32_16x16x32_bf16 v[58:61], v[150:153], v[188:191], v[58:61]
	v_mfma_f32_16x16x32_bf16 v[30:33], v[158:161], v[188:191], v[30:33]
	v_mfma_f32_16x16x32_bf16 v[54:57], v[150:153], v[196:199], v[54:57]
	v_mfma_f32_16x16x32_bf16 v[22:25], v[158:161], v[196:199], v[22:25]
	v_mfma_f32_16x16x32_bf16 v[50:53], v[150:153], v[210:213], v[50:53]
	v_mfma_f32_16x16x32_bf16 v[18:21], v[158:161], v[210:213], v[18:21]
	s_barrier
	s_add_i32 s18, s33, s24
	v_lshl_add_u64 v[170:171], v[170:171], 0, s[56:57]
	s_mov_b32 m0, s18
	ds_read_b128 v[162:165], v208 offset:49152
	ds_read_b128 v[166:169], v208 offset:50176
	ds_read_b128 v[184:187], v208 offset:51200
	ds_read_b128 v[188:191], v208 offset:52224
	ds_read_b128 v[192:195], v208 offset:53248
	ds_read_b128 v[196:199], v208 offset:54272
	ds_read_b128 v[200:203], v208 offset:55296
	ds_read_b128 v[210:213], v208 offset:56320
	global_load_lds_dwordx4 v[170:171], off
	s_add_i32 m0, s18, 0x2000
	s_add_u32 s16, s16, 0x80080
	v_lshl_add_u64 v[170:171], v[172:173], 0, s[56:57]
	s_addc_u32 s17, s17, 0
	s_add_i32 s18, s45, s24
	global_load_lds_dwordx4 v[170:171], off
	v_lshl_add_u64 v[170:171], s[16:17], 0, v[178:179]
	s_mov_b32 m0, s18
	s_nop 0
	global_load_lds_dwordx4 v[170:171], off
	v_lshl_add_u64 v[170:171], s[16:17], 0, v[176:177]
	s_add_i32 m0, s18, 0x2000
	s_nop 0
	global_load_lds_dwordx4 v[170:171], off
	v_lshl_add_u64 v[170:171], v[204:205], 0, s[56:57]
	s_mov_b32 m0, s35
	s_nop 0
	global_load_lds_dwordx4 v[170:171], off
	v_lshl_add_u64 v[170:171], v[214:215], 0, s[56:57]
	s_mov_b32 m0, s36
	s_nop 0
	global_load_lds_dwordx4 v[170:171], off
	s_waitcnt vmcnt(8)
	s_waitcnt lgkmcnt(0)
	s_barrier
	s_waitcnt lgkmcnt(0)
	v_mfma_f32_16x16x32_bf16 v[110:113], v[130:133], v[162:165], v[110:113]
	v_mfma_f32_16x16x32_bf16 v[78:81], v[138:141], v[162:165], v[78:81]
	v_mfma_f32_16x16x32_bf16 v[106:109], v[130:133], v[184:187], v[106:109]
	v_mfma_f32_16x16x32_bf16 v[74:77], v[138:141], v[184:187], v[74:77]
	v_mfma_f32_16x16x32_bf16 v[102:105], v[130:133], v[192:195], v[102:105]
	v_mfma_f32_16x16x32_bf16 v[70:73], v[138:141], v[192:195], v[70:73]
	v_mfma_f32_16x16x32_bf16 v[98:101], v[130:133], v[200:203], v[98:101]
	v_mfma_f32_16x16x32_bf16 v[62:65], v[138:141], v[200:203], v[62:65]
	v_mfma_f32_16x16x32_bf16 v[110:113], v[134:137], v[166:169], v[110:113]
	v_mfma_f32_16x16x32_bf16 v[78:81], v[142:145], v[166:169], v[78:81]
	v_mfma_f32_16x16x32_bf16 v[106:109], v[134:137], v[188:191], v[106:109]
	v_mfma_f32_16x16x32_bf16 v[74:77], v[142:145], v[188:191], v[74:77]
	v_mfma_f32_16x16x32_bf16 v[102:105], v[134:137], v[196:199], v[102:105]
	v_mfma_f32_16x16x32_bf16 v[70:73], v[142:145], v[196:199], v[70:73]
	v_mfma_f32_16x16x32_bf16 v[98:101], v[134:137], v[210:213], v[98:101]
	v_mfma_f32_16x16x32_bf16 v[62:65], v[142:145], v[210:213], v[62:65]
	v_mfma_f32_16x16x32_bf16 v[46:49], v[146:149], v[162:165], v[46:49]
	v_mfma_f32_16x16x32_bf16 v[12:15], v[154:157], v[162:165], v[12:15]
	v_mfma_f32_16x16x32_bf16 v[38:41], v[146:149], v[184:187], v[38:41]
	v_mfma_f32_16x16x32_bf16 v[8:11], v[154:157], v[184:187], v[8:11]
	v_mfma_f32_16x16x32_bf16 v[34:37], v[146:149], v[192:195], v[34:37]
	v_mfma_f32_16x16x32_bf16 v[4:7], v[154:157], v[192:195], v[4:7]
	v_mfma_f32_16x16x32_bf16 v[26:29], v[146:149], v[200:203], v[26:29]
	v_mfma_f32_16x16x32_bf16 v[0:3], v[154:157], v[200:203], v[0:3]
	v_mfma_f32_16x16x32_bf16 v[46:49], v[150:153], v[166:169], v[46:49]
	v_mfma_f32_16x16x32_bf16 v[12:15], v[158:161], v[166:169], v[12:15]
	v_mfma_f32_16x16x32_bf16 v[38:41], v[150:153], v[188:191], v[38:41]
	v_mfma_f32_16x16x32_bf16 v[8:11], v[158:161], v[188:191], v[8:11]
	v_mfma_f32_16x16x32_bf16 v[34:37], v[150:153], v[196:199], v[34:37]
	v_mfma_f32_16x16x32_bf16 v[4:7], v[158:161], v[196:199], v[4:7]
	v_mfma_f32_16x16x32_bf16 v[26:29], v[150:153], v[210:213], v[26:29]
	v_mfma_f32_16x16x32_bf16 v[0:3], v[158:161], v[210:213], v[0:3]
	s_barrier
	s_add_i32 s44, s44, 2
	s_add_u32 s14, s14, 0x100
	s_addc_u32 s15, s15, 0
	s_add_u32 s42, s42, 0x100
	s_addc_u32 s43, s43, 0
	s_cmp_gt_u32 s44, 29
	s_cbranch_scc0 .LBB0_108
	s_setprio 0
	s_and_b64 vcc, exec, s[2:3]
	s_movk_i32 s44, 0x1000
	s_cbranch_vccz .LBB0_111
	s_barrier

.LBB0_551:
	s_ashr_i32 s19, s18, 31
	s_lshl_b64 s[20:21], s[18:19], 18
	s_add_u32 s17, s0, s20
	s_addc_u32 s19, s1, s21
	s_cmp_gt_i32 s16, 1
	s_cselect_b32 s20, 0x2000000, 0
	s_add_u32 s20, s17, s20
	s_addc_u32 s21, s19, 0
	s_and_b64 s[22:23], s[4:5], exec
	s_cselect_b32 s19, s21, s7
	s_cselect_b32 s42, s20, s6
	s_ashr_i32 s17, s16, 31
	s_lshl_b64 s[22:23], s[16:17], 18
	s_add_u32 s22, s28, s22
	s_addc_u32 s23, s29, s23
	s_and_b64 s[24:25], s[4:5], exec
	s_cselect_b32 s17, s23, s9
	s_cselect_b32 s43, s22, s8
	s_add_u32 s6, s6, 0x20080
	s_addc_u32 s7, s7, 0
	s_add_u32 s44, s8, 0x100
	v_mov_b32_e32 v0, 0
	s_addc_u32 s45, s9, 0
	s_mov_b32 s46, -2
	v_mov_b32_e32 v1, v0
	v_mov_b32_e32 v2, v0
	v_mov_b32_e32 v3, v0
	v_mov_b32_e32 v4, v0
	v_mov_b32_e32 v5, v0
	v_mov_b32_e32 v6, v0
	v_mov_b32_e32 v7, v0
	v_mov_b32_e32 v8, v0
	v_mov_b32_e32 v9, v0
	v_mov_b32_e32 v10, v0
	v_mov_b32_e32 v11, v0
	v_mov_b32_e32 v12, v0
	v_mov_b32_e32 v13, v0
	v_mov_b32_e32 v14, v0
	v_mov_b32_e32 v15, v0
	v_mov_b32_e32 v18, v0
	v_mov_b32_e32 v19, v0
	v_mov_b32_e32 v20, v0
	v_mov_b32_e32 v21, v0
	v_mov_b32_e32 v22, v0
	v_mov_b32_e32 v23, v0
	v_mov_b32_e32 v24, v0
	v_mov_b32_e32 v25, v0
	v_mov_b32_e32 v26, v0
	v_mov_b32_e32 v27, v0
	v_mov_b32_e32 v28, v0
	v_mov_b32_e32 v29, v0
	v_mov_b32_e32 v30, v0
	v_mov_b32_e32 v31, v0
	v_mov_b32_e32 v32, v0
	v_mov_b32_e32 v33, v0
	s_waitcnt vmcnt(0)
	v_mov_b32_e32 v78, v0
	v_mov_b32_e32 v79, v0
	v_mov_b32_e32 v80, v0
	v_mov_b32_e32 v81, v0
	v_mov_b32_e32 v82, v0
	v_mov_b32_e32 v83, v0
	v_mov_b32_e32 v84, v0
	v_mov_b32_e32 v85, v0
	v_mov_b32_e32 v90, v0
	v_mov_b32_e32 v91, v0
	v_mov_b32_e32 v92, v0
	v_mov_b32_e32 v93, v0
	v_mov_b32_e32 v94, v0
	v_mov_b32_e32 v95, v0
	v_mov_b32_e32 v96, v0
	v_mov_b32_e32 v97, v0
	v_mov_b32_e32 v98, v0
	v_mov_b32_e32 v99, v0
	v_mov_b32_e32 v100, v0
	v_mov_b32_e32 v101, v0
	v_mov_b32_e32 v102, v0
	v_mov_b32_e32 v103, v0
	v_mov_b32_e32 v104, v0
	v_mov_b32_e32 v105, v0
	v_mov_b32_e32 v106, v0
	v_mov_b32_e32 v107, v0
	v_mov_b32_e32 v108, v0
	v_mov_b32_e32 v109, v0
	v_mov_b32_e32 v110, v0
	v_mov_b32_e32 v111, v0
	v_mov_b32_e32 v112, v0
	v_mov_b32_e32 v113, v0
	v_mov_b32_e32 v34, v0
	v_mov_b32_e32 v35, v0
	v_mov_b32_e32 v36, v0
	v_mov_b32_e32 v37, v0
	v_mov_b32_e32 v38, v0
	v_mov_b32_e32 v39, v0
	v_mov_b32_e32 v40, v0
	v_mov_b32_e32 v41, v0
	v_mov_b32_e32 v42, v0
	v_mov_b32_e32 v43, v0
	v_mov_b32_e32 v44, v0
	v_mov_b32_e32 v45, v0
	v_mov_b32_e32 v46, v0
	v_mov_b32_e32 v47, v0
	v_mov_b32_e32 v48, v0
	v_mov_b32_e32 v49, v0
	v_mov_b32_e32 v50, v0
	v_mov_b32_e32 v51, v0
	v_mov_b32_e32 v52, v0
	v_mov_b32_e32 v53, v0
	v_mov_b32_e32 v54, v0
	v_mov_b32_e32 v55, v0
	v_mov_b32_e32 v56, v0
	v_mov_b32_e32 v57, v0
	v_mov_b32_e32 v62, v0
	v_mov_b32_e32 v63, v0
	v_mov_b32_e32 v64, v0
	v_mov_b32_e32 v65, v0
	v_mov_b32_e32 v66, v0
	v_mov_b32_e32 v67, v0
	v_mov_b32_e32 v68, v0
	v_mov_b32_e32 v69, v0
	v_mov_b32_e32 v114, v0
	v_mov_b32_e32 v115, v0
	v_mov_b32_e32 v116, v0
	v_mov_b32_e32 v117, v0
	v_mov_b32_e32 v118, v0
	v_mov_b32_e32 v119, v0
	v_mov_b32_e32 v120, v0
	v_mov_b32_e32 v121, v0
	v_mov_b32_e32 v130, v0
	v_mov_b32_e32 v131, v0
	v_mov_b32_e32 v132, v0
	v_mov_b32_e32 v133, v0
	v_mov_b32_e32 v134, v0
	v_mov_b32_e32 v135, v0
	v_mov_b32_e32 v136, v0
	v_mov_b32_e32 v137, v0
	v_mov_b32_e32 v138, v0
	v_mov_b32_e32 v139, v0
	v_mov_b32_e32 v140, v0
	v_mov_b32_e32 v141, v0
	v_mov_b32_e32 v142, v0
	v_mov_b32_e32 v143, v0
	v_mov_b32_e32 v144, v0
	v_mov_b32_e32 v145, v0
	v_mov_b32_e32 v146, v0
	v_mov_b32_e32 v147, v0
	v_mov_b32_e32 v148, v0
	v_mov_b32_e32 v149, v0
	v_mov_b32_e32 v150, v0
	v_mov_b32_e32 v151, v0
	v_mov_b32_e32 v152, v0
	v_mov_b32_e32 v153, v0
	v_readlane_b32 s100, v253, 1
	s_cmp_ge_u32 s100, 4
	s_cbranch_scc1 .Lprio_3
	s_setprio 1
.Lprio_3:
.LBB0_552:
	s_add_u32 s8, s6, 0xfffe0080
	s_addc_u32 s9, s7, -1
	s_add_i32 s47, 0, 0x10000
	s_cmp_eq_u32 s46, 4
	s_cselect_b32 s25, s19, s9
	s_cselect_b32 s24, s42, s8
	s_cselect_b32 s9, s17, s45
	s_cselect_b32 s8, s43, s44
	s_add_i32 s50, 0, 0x14000
	v_add_u32_e32 v86, s47, v184
	v_add_u32_e32 v168, s50, v184
	ds_read_b128 v[58:61], v86
	ds_read_b128 v[70:73], v86 offset:1024
	ds_read_b128 v[74:77], v86 offset:2048
	ds_read_b128 v[86:89], v86 offset:3072
	ds_read_b128 v[122:125], v168
	ds_read_b128 v[126:129], v168 offset:1024
	ds_read_b128 v[154:157], v168 offset:2048
	ds_read_b128 v[176:179], v168 offset:3072
	v_lshl_add_u64 v[168:169], s[6:7], 0, v[164:165]
	s_add_i32 m0, s31, 0xc000
	ds_read_b128 v[186:189], v185
	ds_read_b128 v[190:193], v185 offset:1024
	ds_read_b128 v[194:197], v185 offset:2048
	ds_read_b128 v[198:201], v185 offset:3072
	ds_read_b128 v[202:205], v185 offset:4096
	ds_read_b128 v[206:209], v185 offset:5120
	ds_read_b128 v[210:213], v185 offset:6144
	ds_read_b128 v[230:233], v185 offset:7168
	global_load_lds_dwordx4 v[168:169], off
	v_lshl_add_u64 v[168:169], s[6:7], 0, v[166:167]
	s_add_i32 m0, s31, 0xe000
	s_nop 0
	global_load_lds_dwordx4 v[168:169], off
	s_waitcnt vmcnt(8)
	s_waitcnt lgkmcnt(0)
	s_barrier
	s_waitcnt lgkmcnt(0)
	v_mfma_f32_16x16x32_bf16 v[150:153], v[58:61], v[186:189], v[150:153]
	v_mfma_f32_16x16x32_bf16 v[146:149], v[74:77], v[186:189], v[146:149]
	v_mfma_f32_16x16x32_bf16 v[142:145], v[58:61], v[194:197], v[142:145]
	v_mfma_f32_16x16x32_bf16 v[138:141], v[74:77], v[194:197], v[138:141]
	v_mfma_f32_16x16x32_bf16 v[134:137], v[58:61], v[202:205], v[134:137]
	v_mfma_f32_16x16x32_bf16 v[130:133], v[74:77], v[202:205], v[130:133]
	v_mfma_f32_16x16x32_bf16 v[118:121], v[58:61], v[210:213], v[118:121]
	v_mfma_f32_16x16x32_bf16 v[114:117], v[74:77], v[210:213], v[114:117]
	v_mfma_f32_16x16x32_bf16 v[150:153], v[70:73], v[190:193], v[150:153]
	v_mfma_f32_16x16x32_bf16 v[146:149], v[86:89], v[190:193], v[146:149]
	v_mfma_f32_16x16x32_bf16 v[142:145], v[70:73], v[198:201], v[142:145]
	v_mfma_f32_16x16x32_bf16 v[138:141], v[86:89], v[198:201], v[138:141]
	v_mfma_f32_16x16x32_bf16 v[134:137], v[70:73], v[206:209], v[134:137]
	v_mfma_f32_16x16x32_bf16 v[130:133], v[86:89], v[206:209], v[130:133]
	v_mfma_f32_16x16x32_bf16 v[118:121], v[70:73], v[230:233], v[118:121]
	v_mfma_f32_16x16x32_bf16 v[114:117], v[86:89], v[230:233], v[114:117]
	v_mfma_f32_16x16x32_bf16 v[66:69], v[122:125], v[186:189], v[66:69]
	v_mfma_f32_16x16x32_bf16 v[62:65], v[154:157], v[186:189], v[62:65]
	v_mfma_f32_16x16x32_bf16 v[54:57], v[122:125], v[194:197], v[54:57]
	v_mfma_f32_16x16x32_bf16 v[50:53], v[154:157], v[194:197], v[50:53]
	v_mfma_f32_16x16x32_bf16 v[46:49], v[122:125], v[202:205], v[46:49]
	v_mfma_f32_16x16x32_bf16 v[42:45], v[154:157], v[202:205], v[42:45]
	v_mfma_f32_16x16x32_bf16 v[38:41], v[122:125], v[210:213], v[38:41]
	v_mfma_f32_16x16x32_bf16 v[34:37], v[154:157], v[210:213], v[34:37]
	v_mfma_f32_16x16x32_bf16 v[66:69], v[126:129], v[190:193], v[66:69]
	v_mfma_f32_16x16x32_bf16 v[62:65], v[176:179], v[190:193], v[62:65]
	v_mfma_f32_16x16x32_bf16 v[54:57], v[126:129], v[198:201], v[54:57]
	v_mfma_f32_16x16x32_bf16 v[50:53], v[176:179], v[198:201], v[50:53]
	v_mfma_f32_16x16x32_bf16 v[46:49], v[126:129], v[206:209], v[46:49]
	v_mfma_f32_16x16x32_bf16 v[42:45], v[176:179], v[206:209], v[42:45]
	v_mfma_f32_16x16x32_bf16 v[38:41], v[126:129], v[230:233], v[38:41]
	v_mfma_f32_16x16x32_bf16 v[34:37], v[176:179], v[230:233], v[34:37]
	s_barrier
	s_add_i32 s47, s47, s30
	v_lshl_add_u64 v[168:169], s[8:9], 0, v[16:17]
	s_mov_b32 m0, s47
	ds_read_b128 v[186:189], v185 offset:16384
	ds_read_b128 v[190:193], v185 offset:17408
	ds_read_b128 v[194:197], v185 offset:18432
	ds_read_b128 v[198:201], v185 offset:19456
	ds_read_b128 v[202:205], v185 offset:20480
	ds_read_b128 v[206:209], v185 offset:21504
	ds_read_b128 v[210:213], v185 offset:22528
	ds_read_b128 v[230:233], v185 offset:23552
	global_load_lds_dwordx4 v[168:169], off
	s_add_i32 m0, s47, 0x2000
	s_add_u32 s48, s8, 0x20000
	v_lshl_add_u64 v[170:171], s[8:9], 0, v[158:159]
	s_addc_u32 s49, s9, 0
	s_add_i32 s47, s50, s30
	global_load_lds_dwordx4 v[170:171], off
	v_lshl_add_u64 v[172:173], s[48:49], 0, v[16:17]
	s_mov_b32 m0, s47
	v_lshl_add_u64 v[180:181], s[24:25], 0, v[160:161]
	global_load_lds_dwordx4 v[172:173], off
	v_lshl_add_u64 v[172:173], s[48:49], 0, v[158:159]
	s_add_i32 m0, s47, 0x2000
	s_nop 0
	global_load_lds_dwordx4 v[172:173], off
	v_lshl_add_u64 v[172:173], s[24:25], 0, v[162:163]
	s_mov_b32 m0, s31
	s_nop 0
	global_load_lds_dwordx4 v[172:173], off
	s_mov_b32 m0, s34
	s_nop 0
	global_load_lds_dwordx4 v[180:181], off
	s_waitcnt vmcnt(8)
	s_waitcnt lgkmcnt(0)
	s_barrier
	s_waitcnt lgkmcnt(0)
	v_mfma_f32_16x16x32_bf16 v[110:113], v[58:61], v[186:189], v[110:113]
	v_mfma_f32_16x16x32_bf16 v[106:109], v[74:77], v[186:189], v[106:109]
	v_mfma_f32_16x16x32_bf16 v[102:105], v[58:61], v[194:197], v[102:105]
	v_mfma_f32_16x16x32_bf16 v[98:101], v[74:77], v[194:197], v[98:101]
	v_mfma_f32_16x16x32_bf16 v[94:97], v[58:61], v[202:205], v[94:97]
	v_mfma_f32_16x16x32_bf16 v[90:93], v[74:77], v[202:205], v[90:93]
	v_mfma_f32_16x16x32_bf16 v[58:61], v[58:61], v[210:213], v[82:85]
	v_mfma_f32_16x16x32_bf16 v[110:113], v[70:73], v[190:193], v[110:113]
	v_mfma_f32_16x16x32_bf16 v[106:109], v[86:89], v[190:193], v[106:109]
	v_mfma_f32_16x16x32_bf16 v[102:105], v[70:73], v[198:201], v[102:105]
	v_mfma_f32_16x16x32_bf16 v[98:101], v[86:89], v[198:201], v[98:101]
	v_mfma_f32_16x16x32_bf16 v[94:97], v[70:73], v[206:209], v[94:97]
	v_mfma_f32_16x16x32_bf16 v[90:93], v[86:89], v[206:209], v[90:93]
	v_mfma_f32_16x16x32_bf16 v[58:61], v[70:73], v[230:233], v[58:61]
	v_mfma_f32_16x16x32_bf16 v[70:73], v[74:77], v[210:213], v[78:81]
	v_mfma_f32_16x16x32_bf16 v[70:73], v[86:89], v[230:233], v[70:73]
	v_mfma_f32_16x16x32_bf16 v[30:33], v[122:125], v[186:189], v[30:33]
	v_mfma_f32_16x16x32_bf16 v[26:29], v[154:157], v[186:189], v[26:29]
	v_mfma_f32_16x16x32_bf16 v[22:25], v[122:125], v[194:197], v[22:25]
	v_mfma_f32_16x16x32_bf16 v[18:21], v[154:157], v[194:197], v[18:21]
	v_mfma_f32_16x16x32_bf16 v[12:15], v[122:125], v[202:205], v[12:15]
	v_mfma_f32_16x16x32_bf16 v[8:11], v[154:157], v[202:205], v[8:11]
	v_mfma_f32_16x16x32_bf16 v[4:7], v[122:125], v[210:213], v[4:7]
	v_mfma_f32_16x16x32_bf16 v[0:3], v[154:157], v[210:213], v[0:3]
	v_mfma_f32_16x16x32_bf16 v[30:33], v[126:129], v[190:193], v[30:33]
	v_mfma_f32_16x16x32_bf16 v[26:29], v[176:179], v[190:193], v[26:29]
	v_mfma_f32_16x16x32_bf16 v[22:25], v[126:129], v[198:201], v[22:25]
	v_mfma_f32_16x16x32_bf16 v[18:21], v[176:179], v[198:201], v[18:21]
	v_mfma_f32_16x16x32_bf16 v[12:15], v[126:129], v[206:209], v[12:15]
	v_mfma_f32_16x16x32_bf16 v[8:11], v[176:179], v[206:209], v[8:11]
	v_mfma_f32_16x16x32_bf16 v[4:7], v[126:129], v[230:233], v[4:7]
	v_mfma_f32_16x16x32_bf16 v[0:3], v[176:179], v[230:233], v[0:3]
	s_barrier
	s_add_i32 s47, 0, 0x18000
	v_add_u32_e32 v82, s47, v184
	s_add_i32 s48, 0, 0x1c000
	ds_read_b128 v[74:77], v82
	ds_read_b128 v[78:81], v82 offset:1024
	ds_read_b128 v[86:89], v82 offset:2048
	ds_read_b128 v[122:125], v82 offset:3072
	v_add_u32_e32 v82, s48, v184
	ds_read_b128 v[126:129], v82
	ds_read_b128 v[154:157], v82 offset:1024
	ds_read_b128 v[176:179], v82 offset:2048
	ds_read_b128 v[186:189], v82 offset:3072
	s_add_u32 s24, s24, 0x20000
	s_addc_u32 s25, s25, 0
	s_mov_b32 m0, s35
	v_lshl_add_u64 v[214:215], s[24:25], 0, v[162:163]
	ds_read_b128 v[82:85], v185 offset:32768
	ds_read_b128 v[190:193], v185 offset:33792
	ds_read_b128 v[194:197], v185 offset:34816
	ds_read_b128 v[198:201], v185 offset:35840
	ds_read_b128 v[202:205], v185 offset:36864
	ds_read_b128 v[206:209], v185 offset:37888
	ds_read_b128 v[210:213], v185 offset:38912
	ds_read_b128 v[230:233], v185 offset:39936
	global_load_lds_dwordx4 v[214:215], off
	v_lshl_add_u64 v[214:215], s[24:25], 0, v[160:161]
	s_mov_b32 m0, s36
	s_nop 0
	global_load_lds_dwordx4 v[214:215], off
	s_waitcnt vmcnt(8)
	s_waitcnt lgkmcnt(0)
	s_barrier
	s_waitcnt lgkmcnt(0)
	v_mfma_f32_16x16x32_bf16 v[150:153], v[74:77], v[82:85], v[150:153]
	v_mfma_f32_16x16x32_bf16 v[146:149], v[86:89], v[82:85], v[146:149]
	v_mfma_f32_16x16x32_bf16 v[142:145], v[74:77], v[194:197], v[142:145]
	v_mfma_f32_16x16x32_bf16 v[138:141], v[86:89], v[194:197], v[138:141]
	v_mfma_f32_16x16x32_bf16 v[134:137], v[74:77], v[202:205], v[134:137]
	v_mfma_f32_16x16x32_bf16 v[130:133], v[86:89], v[202:205], v[130:133]
	v_mfma_f32_16x16x32_bf16 v[118:121], v[74:77], v[210:213], v[118:121]
	v_mfma_f32_16x16x32_bf16 v[114:117], v[86:89], v[210:213], v[114:117]
	v_mfma_f32_16x16x32_bf16 v[150:153], v[78:81], v[190:193], v[150:153]
	v_mfma_f32_16x16x32_bf16 v[146:149], v[122:125], v[190:193], v[146:149]
	v_mfma_f32_16x16x32_bf16 v[142:145], v[78:81], v[198:201], v[142:145]
	v_mfma_f32_16x16x32_bf16 v[138:141], v[122:125], v[198:201], v[138:141]
	v_mfma_f32_16x16x32_bf16 v[134:137], v[78:81], v[206:209], v[134:137]
	v_mfma_f32_16x16x32_bf16 v[130:133], v[122:125], v[206:209], v[130:133]
	v_mfma_f32_16x16x32_bf16 v[118:121], v[78:81], v[230:233], v[118:121]
	v_mfma_f32_16x16x32_bf16 v[114:117], v[122:125], v[230:233], v[114:117]
	v_mfma_f32_16x16x32_bf16 v[66:69], v[126:129], v[82:85], v[66:69]
	v_mfma_f32_16x16x32_bf16 v[62:65], v[176:179], v[82:85], v[62:65]
	v_mfma_f32_16x16x32_bf16 v[54:57], v[126:129], v[194:197], v[54:57]
	v_mfma_f32_16x16x32_bf16 v[50:53], v[176:179], v[194:197], v[50:53]
	v_mfma_f32_16x16x32_bf16 v[46:49], v[126:129], v[202:205], v[46:49]
	v_mfma_f32_16x16x32_bf16 v[42:45], v[176:179], v[202:205], v[42:45]
	v_mfma_f32_16x16x32_bf16 v[38:41], v[126:129], v[210:213], v[38:41]
	v_mfma_f32_16x16x32_bf16 v[34:37], v[176:179], v[210:213], v[34:37]
	v_mfma_f32_16x16x32_bf16 v[66:69], v[154:157], v[190:193], v[66:69]
	v_mfma_f32_16x16x32_bf16 v[62:65], v[186:189], v[190:193], v[62:65]
	v_mfma_f32_16x16x32_bf16 v[54:57], v[154:157], v[198:201], v[54:57]
	v_mfma_f32_16x16x32_bf16 v[50:53], v[186:189], v[198:201], v[50:53]
	v_mfma_f32_16x16x32_bf16 v[46:49], v[154:157], v[206:209], v[46:49]
	v_mfma_f32_16x16x32_bf16 v[42:45], v[186:189], v[206:209], v[42:45]
	v_mfma_f32_16x16x32_bf16 v[38:41], v[154:157], v[230:233], v[38:41]
	v_mfma_f32_16x16x32_bf16 v[34:37], v[186:189], v[230:233], v[34:37]
	s_barrier
	s_add_i32 s24, s47, s30
	v_lshl_add_u64 v[82:83], v[168:169], 0, s[56:57]
	s_mov_b32 m0, s24
	ds_read_b128 v[190:193], v185 offset:49152
	ds_read_b128 v[194:197], v185 offset:50176
	ds_read_b128 v[198:201], v185 offset:51200
	ds_read_b128 v[202:205], v185 offset:52224
	ds_read_b128 v[206:209], v185 offset:53248
	ds_read_b128 v[210:213], v185 offset:54272
	ds_read_b128 v[230:233], v185 offset:55296
	ds_read_b128 v[234:237], v185 offset:56320
	global_load_lds_dwordx4 v[82:83], off
	s_add_i32 m0, s24, 0x2000
	s_add_u32 s8, s8, 0x20080
	v_lshl_add_u64 v[82:83], v[170:171], 0, s[56:57]
	s_addc_u32 s9, s9, 0
	s_add_i32 s24, s48, s30
	global_load_lds_dwordx4 v[82:83], off
	v_lshl_add_u64 v[82:83], s[8:9], 0, v[16:17]
	s_mov_b32 m0, s24
	s_nop 0
	global_load_lds_dwordx4 v[82:83], off
	v_lshl_add_u64 v[82:83], s[8:9], 0, v[158:159]
	s_add_i32 m0, s24, 0x2000
	s_nop 0
	global_load_lds_dwordx4 v[82:83], off
	v_lshl_add_u64 v[82:83], v[172:173], 0, s[56:57]
	s_mov_b32 m0, s38
	s_nop 0
	global_load_lds_dwordx4 v[82:83], off
	v_lshl_add_u64 v[82:83], v[180:181], 0, s[56:57]
	s_mov_b32 m0, s39
	s_nop 0
	global_load_lds_dwordx4 v[82:83], off
	s_waitcnt vmcnt(8)
	s_waitcnt lgkmcnt(0)
	s_barrier
	s_waitcnt lgkmcnt(0)
	v_mfma_f32_16x16x32_bf16 v[82:85], v[74:77], v[190:193], v[110:113]
	v_mfma_f32_16x16x32_bf16 v[110:113], v[78:81], v[194:197], v[82:85]
	v_mfma_f32_16x16x32_bf16 v[82:85], v[86:89], v[190:193], v[106:109]
	v_mfma_f32_16x16x32_bf16 v[106:109], v[122:125], v[194:197], v[82:85]
	v_mfma_f32_16x16x32_bf16 v[82:85], v[74:77], v[198:201], v[102:105]
	v_mfma_f32_16x16x32_bf16 v[102:105], v[78:81], v[202:205], v[82:85]
	v_mfma_f32_16x16x32_bf16 v[82:85], v[86:89], v[198:201], v[98:101]
	v_mfma_f32_16x16x32_bf16 v[98:101], v[122:125], v[202:205], v[82:85]
	v_mfma_f32_16x16x32_bf16 v[82:85], v[74:77], v[206:209], v[94:97]
	v_mfma_f32_16x16x32_bf16 v[94:97], v[78:81], v[210:213], v[82:85]
	v_mfma_f32_16x16x32_bf16 v[82:85], v[86:89], v[206:209], v[90:93]
	v_mfma_f32_16x16x32_bf16 v[58:61], v[74:77], v[230:233], v[58:61]
	v_mfma_f32_16x16x32_bf16 v[90:93], v[122:125], v[210:213], v[82:85]
	v_mfma_f32_16x16x32_bf16 v[82:85], v[78:81], v[234:237], v[58:61]
	v_mfma_f32_16x16x32_bf16 v[58:61], v[86:89], v[230:233], v[70:73]
	v_mfma_f32_16x16x32_bf16 v[78:81], v[122:125], v[234:237], v[58:61]
	v_mfma_f32_16x16x32_bf16 v[30:33], v[126:129], v[190:193], v[30:33]
	v_mfma_f32_16x16x32_bf16 v[26:29], v[176:179], v[190:193], v[26:29]
	v_mfma_f32_16x16x32_bf16 v[22:25], v[126:129], v[198:201], v[22:25]
	v_mfma_f32_16x16x32_bf16 v[18:21], v[176:179], v[198:201], v[18:21]
	v_mfma_f32_16x16x32_bf16 v[12:15], v[126:129], v[206:209], v[12:15]
	v_mfma_f32_16x16x32_bf16 v[8:11], v[176:179], v[206:209], v[8:11]
	v_mfma_f32_16x16x32_bf16 v[4:7], v[126:129], v[230:233], v[4:7]
	v_mfma_f32_16x16x32_bf16 v[0:3], v[176:179], v[230:233], v[0:3]
	v_mfma_f32_16x16x32_bf16 v[30:33], v[154:157], v[194:197], v[30:33]
	v_mfma_f32_16x16x32_bf16 v[26:29], v[186:189], v[194:197], v[26:29]
	v_mfma_f32_16x16x32_bf16 v[22:25], v[154:157], v[202:205], v[22:25]
	v_mfma_f32_16x16x32_bf16 v[18:21], v[186:189], v[202:205], v[18:21]
	v_mfma_f32_16x16x32_bf16 v[12:15], v[154:157], v[210:213], v[12:15]
	v_mfma_f32_16x16x32_bf16 v[8:11], v[186:189], v[210:213], v[8:11]
	v_mfma_f32_16x16x32_bf16 v[4:7], v[154:157], v[234:237], v[4:7]
	v_mfma_f32_16x16x32_bf16 v[0:3], v[186:189], v[234:237], v[0:3]
	s_barrier
	s_add_i32 s46, s46, 2
	s_add_u32 s6, s6, 0x100
	s_addc_u32 s7, s7, 0
	s_add_u32 s44, s44, 0x100
	s_addc_u32 s45, s45, 0
	s_cmp_gt_u32 s46, 5
	s_cbranch_scc0 .LBB0_552
	s_setprio 0
	s_and_b64 vcc, exec, s[14:15]
	s_cbranch_vccz .LBB0_555
	s_barrier

.LBB0_1017:
	s_ashr_i32 s19, s18, 31
	s_lshl_b64 s[20:21], s[18:19], 20
	s_add_u32 s20, s34, s20
	s_addc_u32 s21, s35, s21
	s_and_b64 s[22:23], s[4:5], exec
	s_cselect_b32 s19, s21, s25
	s_cselect_b32 s31, s20, s24
	s_ashr_i32 s17, s16, 31
	s_lshl_b64 s[22:23], s[16:17], 20
	s_add_u32 s22, s36, s22
	s_addc_u32 s23, s37, s23
	s_and_b64 s[28:29], s[4:5], exec
	s_cselect_b32 s17, s23, s27
	s_cselect_b32 s55, s22, s26
	s_add_u32 s24, s24, 0x80080
	s_addc_u32 s25, s25, 0
	s_add_u32 s60, s26, 0x100
	v_mov_b32_e32 v50, 0
	s_addc_u32 s61, s27, 0
	s_mov_b32 s62, -2
	v_mov_b32_e32 v51, v50
	v_mov_b32_e32 v52, v50
	v_mov_b32_e32 v53, v50
	v_mov_b32_e32 v70, v50
	v_mov_b32_e32 v71, v50
	v_mov_b32_e32 v72, v50
	v_mov_b32_e32 v73, v50
	v_mov_b32_e32 v74, v50
	v_mov_b32_e32 v75, v50
	v_mov_b32_e32 v76, v50
	v_mov_b32_e32 v77, v50
	v_mov_b32_e32 v78, v50
	v_mov_b32_e32 v79, v50
	v_mov_b32_e32 v80, v50
	v_mov_b32_e32 v81, v50
	v_mov_b32_e32 v82, v50
	v_mov_b32_e32 v83, v50
	v_mov_b32_e32 v84, v50
	v_mov_b32_e32 v85, v50
	v_mov_b32_e32 v86, v50
	v_mov_b32_e32 v87, v50
	v_mov_b32_e32 v88, v50
	v_mov_b32_e32 v89, v50
	v_mov_b32_e32 v90, v50
	v_mov_b32_e32 v91, v50
	v_mov_b32_e32 v92, v50
	v_mov_b32_e32 v93, v50
	v_mov_b32_e32 v94, v50
	v_mov_b32_e32 v95, v50
	v_mov_b32_e32 v96, v50
	v_mov_b32_e32 v97, v50
	v_mov_b32_e32 v0, v50
	v_mov_b32_e32 v1, v50
	v_mov_b32_e32 v2, v50
	v_mov_b32_e32 v3, v50
	v_mov_b32_e32 v4, v50
	v_mov_b32_e32 v5, v50
	v_mov_b32_e32 v6, v50
	v_mov_b32_e32 v7, v50
	v_mov_b32_e32 v8, v50
	v_mov_b32_e32 v9, v50
	v_mov_b32_e32 v10, v50
	v_mov_b32_e32 v11, v50
	v_mov_b32_e32 v12, v50
	v_mov_b32_e32 v13, v50
	v_mov_b32_e32 v14, v50
	v_mov_b32_e32 v15, v50
	v_mov_b32_e32 v18, v50
	v_mov_b32_e32 v19, v50
	v_mov_b32_e32 v20, v50
	v_mov_b32_e32 v21, v50
	v_mov_b32_e32 v22, v50
	v_mov_b32_e32 v23, v50
	v_mov_b32_e32 v24, v50
	v_mov_b32_e32 v25, v50
	v_mov_b32_e32 v26, v50
	v_mov_b32_e32 v27, v50
	v_mov_b32_e32 v28, v50
	v_mov_b32_e32 v29, v50
	v_mov_b32_e32 v30, v50
	v_mov_b32_e32 v31, v50
	v_mov_b32_e32 v32, v50
	v_mov_b32_e32 v33, v50
	v_mov_b32_e32 v98, v50
	v_mov_b32_e32 v99, v50
	v_mov_b32_e32 v100, v50
	v_mov_b32_e32 v101, v50
	v_mov_b32_e32 v102, v50
	v_mov_b32_e32 v103, v50
	v_mov_b32_e32 v104, v50
	v_mov_b32_e32 v105, v50
	v_mov_b32_e32 v106, v50
	v_mov_b32_e32 v107, v50
	v_mov_b32_e32 v108, v50
	v_mov_b32_e32 v109, v50
	v_mov_b32_e32 v110, v50
	v_mov_b32_e32 v111, v50
	v_mov_b32_e32 v112, v50
	v_mov_b32_e32 v113, v50
	v_mov_b32_e32 v114, v50
	v_mov_b32_e32 v115, v50
	v_mov_b32_e32 v116, v50
	v_mov_b32_e32 v117, v50
	v_mov_b32_e32 v118, v50
	v_mov_b32_e32 v119, v50
	v_mov_b32_e32 v120, v50
	v_mov_b32_e32 v121, v50
	v_mov_b32_e32 v122, v50
	v_mov_b32_e32 v123, v50
	v_mov_b32_e32 v124, v50
	v_mov_b32_e32 v125, v50
	v_mov_b32_e32 v126, v50
	v_mov_b32_e32 v127, v50
	v_mov_b32_e32 v128, v50
	v_mov_b32_e32 v129, v50
	v_mov_b32_e32 v34, v50
	v_mov_b32_e32 v35, v50
	v_mov_b32_e32 v36, v50
	v_mov_b32_e32 v37, v50
	v_mov_b32_e32 v38, v50
	v_mov_b32_e32 v39, v50
	v_mov_b32_e32 v40, v50
	v_mov_b32_e32 v41, v50
	v_mov_b32_e32 v42, v50
	v_mov_b32_e32 v43, v50
	v_mov_b32_e32 v44, v50
	v_mov_b32_e32 v45, v50
	v_mov_b32_e32 v46, v50
	v_mov_b32_e32 v47, v50
	v_mov_b32_e32 v48, v50
	v_mov_b32_e32 v49, v50
	v_mov_b32_e32 v54, v50
	v_mov_b32_e32 v55, v50
	v_mov_b32_e32 v56, v50
	v_mov_b32_e32 v57, v50
	v_mov_b32_e32 v58, v50
	v_mov_b32_e32 v59, v50
	v_mov_b32_e32 v60, v50
	v_mov_b32_e32 v61, v50
	v_mov_b32_e32 v62, v50
	v_mov_b32_e32 v63, v50
	v_mov_b32_e32 v64, v50
	v_mov_b32_e32 v65, v50
	v_mov_b32_e32 v66, v50
	v_mov_b32_e32 v67, v50
	v_mov_b32_e32 v68, v50
	v_mov_b32_e32 v69, v50
	v_readlane_b32 s100, v253, 1
	s_cmp_ge_u32 s100, 4
	s_cbranch_scc1 .Lprio_4
	s_setprio 1
.Lprio_4:
.LBB0_1018:
	s_add_u32 s26, s24, 0xfff80080
	s_addc_u32 s27, s25, -1
	s_add_i32 s63, 0, 0x10000
	s_cmp_eq_u32 s62, 28
	s_cselect_b32 s29, s19, s27
	s_cselect_b32 s28, s31, s26
	v_add_u32_e32 v16, s63, v166
	s_cselect_b32 s27, s17, s61
	s_cselect_b32 s26, s55, s60
	s_add_i32 s66, 0, 0x14000
	ds_read_b128 v[144:147], v16
	ds_read_b128 v[148:151], v16 offset:1024
	ds_read_b128 v[152:155], v16 offset:2048
	ds_read_b128 v[156:159], v16 offset:3072
	v_add_u32_e32 v16, s66, v166
	ds_read_b128 v[160:163], v16
	ds_read_b128 v[176:179], v16 offset:1024
	ds_read_b128 v[180:183], v16 offset:2048
	ds_read_b128 v[184:187], v16 offset:3072
	v_lshl_add_u64 v[168:169], s[24:25], 0, v[140:141]
	s_add_i32 m0, s39, 0xc000
	ds_read_b128 v[188:191], v167
	ds_read_b128 v[192:195], v167 offset:1024
	ds_read_b128 v[196:199], v167 offset:2048
	ds_read_b128 v[200:203], v167 offset:3072
	ds_read_b128 v[204:207], v167 offset:4096
	ds_read_b128 v[208:211], v167 offset:5120
	ds_read_b128 v[212:215], v167 offset:6144
	ds_read_b128 v[230:233], v167 offset:7168
	global_load_lds_dwordx4 v[168:169], off
	v_lshl_add_u64 v[168:169], s[24:25], 0, v[142:143]
	s_add_i32 m0, s39, 0xe000
	s_nop 0
	global_load_lds_dwordx4 v[168:169], off
	s_waitcnt vmcnt(8)
	s_waitcnt lgkmcnt(0)
	s_barrier
	s_waitcnt lgkmcnt(0)
	v_mfma_f32_16x16x32_bf16 v[66:69], v[144:147], v[188:191], v[66:69]
	v_mfma_f32_16x16x32_bf16 v[62:65], v[152:155], v[188:191], v[62:65]
	v_mfma_f32_16x16x32_bf16 v[58:61], v[144:147], v[196:199], v[58:61]
	v_mfma_f32_16x16x32_bf16 v[54:57], v[152:155], v[196:199], v[54:57]
	v_mfma_f32_16x16x32_bf16 v[46:49], v[144:147], v[204:207], v[46:49]
	v_mfma_f32_16x16x32_bf16 v[42:45], v[152:155], v[204:207], v[42:45]
	v_mfma_f32_16x16x32_bf16 v[38:41], v[144:147], v[212:215], v[38:41]
	v_mfma_f32_16x16x32_bf16 v[34:37], v[152:155], v[212:215], v[34:37]
	v_mfma_f32_16x16x32_bf16 v[66:69], v[148:151], v[192:195], v[66:69]
	v_mfma_f32_16x16x32_bf16 v[62:65], v[156:159], v[192:195], v[62:65]
	v_mfma_f32_16x16x32_bf16 v[58:61], v[148:151], v[200:203], v[58:61]
	v_mfma_f32_16x16x32_bf16 v[54:57], v[156:159], v[200:203], v[54:57]
	v_mfma_f32_16x16x32_bf16 v[46:49], v[148:151], v[208:211], v[46:49]
	v_mfma_f32_16x16x32_bf16 v[42:45], v[156:159], v[208:211], v[42:45]
	v_mfma_f32_16x16x32_bf16 v[38:41], v[148:151], v[230:233], v[38:41]
	v_mfma_f32_16x16x32_bf16 v[34:37], v[156:159], v[230:233], v[34:37]
	v_mfma_f32_16x16x32_bf16 v[126:129], v[160:163], v[188:191], v[126:129]
	v_mfma_f32_16x16x32_bf16 v[122:125], v[180:183], v[188:191], v[122:125]
	v_mfma_f32_16x16x32_bf16 v[118:121], v[160:163], v[196:199], v[118:121]
	v_mfma_f32_16x16x32_bf16 v[114:117], v[180:183], v[196:199], v[114:117]
	v_mfma_f32_16x16x32_bf16 v[110:113], v[160:163], v[204:207], v[110:113]
	v_mfma_f32_16x16x32_bf16 v[106:109], v[180:183], v[204:207], v[106:109]
	v_mfma_f32_16x16x32_bf16 v[102:105], v[160:163], v[212:215], v[102:105]
	v_mfma_f32_16x16x32_bf16 v[98:101], v[180:183], v[212:215], v[98:101]
	v_mfma_f32_16x16x32_bf16 v[126:129], v[176:179], v[192:195], v[126:129]
	v_mfma_f32_16x16x32_bf16 v[122:125], v[184:187], v[192:195], v[122:125]
	v_mfma_f32_16x16x32_bf16 v[118:121], v[176:179], v[200:203], v[118:121]
	v_mfma_f32_16x16x32_bf16 v[114:117], v[184:187], v[200:203], v[114:117]
	v_mfma_f32_16x16x32_bf16 v[110:113], v[176:179], v[208:211], v[110:113]
	v_mfma_f32_16x16x32_bf16 v[106:109], v[184:187], v[208:211], v[106:109]
	v_mfma_f32_16x16x32_bf16 v[102:105], v[176:179], v[230:233], v[102:105]
	v_mfma_f32_16x16x32_bf16 v[98:101], v[184:187], v[230:233], v[98:101]
	s_barrier
	s_add_i32 s63, s63, s38
	v_lshl_add_u64 v[168:169], s[26:27], 0, v[132:133]
	s_mov_b32 m0, s63
	ds_read_b128 v[188:191], v167 offset:16384
	ds_read_b128 v[192:195], v167 offset:17408
	ds_read_b128 v[196:199], v167 offset:18432
	ds_read_b128 v[200:203], v167 offset:19456
	ds_read_b128 v[204:207], v167 offset:20480
	ds_read_b128 v[208:211], v167 offset:21504
	ds_read_b128 v[212:215], v167 offset:22528
	ds_read_b128 v[230:233], v167 offset:23552
	global_load_lds_dwordx4 v[168:169], off
	s_add_i32 m0, s63, 0x2000
	s_add_u32 s64, s26, 0x80000
	v_lshl_add_u64 v[170:171], s[26:27], 0, v[136:137]
	s_addc_u32 s65, s27, 0
	s_add_i32 s63, s66, s38
	global_load_lds_dwordx4 v[170:171], off
	v_lshl_add_u64 v[172:173], s[64:65], 0, v[132:133]
	s_mov_b32 m0, s63
	v_lshl_add_u64 v[222:223], s[28:29], 0, v[134:135]
	global_load_lds_dwordx4 v[172:173], off
	v_lshl_add_u64 v[172:173], s[64:65], 0, v[136:137]
	s_add_i32 m0, s63, 0x2000
	s_nop 0
	global_load_lds_dwordx4 v[172:173], off
	v_lshl_add_u64 v[172:173], s[28:29], 0, v[130:131]
	s_mov_b32 m0, s39
	s_nop 0
	global_load_lds_dwordx4 v[172:173], off
	s_mov_b32 m0, s40
	s_nop 0
	global_load_lds_dwordx4 v[222:223], off
	s_waitcnt vmcnt(8)
	s_waitcnt lgkmcnt(0)
	s_barrier
	s_waitcnt lgkmcnt(0)
	v_mfma_f32_16x16x32_bf16 v[30:33], v[144:147], v[188:191], v[30:33]
	v_mfma_f32_16x16x32_bf16 v[26:29], v[152:155], v[188:191], v[26:29]
	v_mfma_f32_16x16x32_bf16 v[22:25], v[144:147], v[196:199], v[22:25]
	v_mfma_f32_16x16x32_bf16 v[18:21], v[152:155], v[196:199], v[18:21]
	v_mfma_f32_16x16x32_bf16 v[12:15], v[144:147], v[204:207], v[12:15]
	v_mfma_f32_16x16x32_bf16 v[8:11], v[152:155], v[204:207], v[8:11]
	v_mfma_f32_16x16x32_bf16 v[4:7], v[144:147], v[212:215], v[4:7]
	v_mfma_f32_16x16x32_bf16 v[0:3], v[152:155], v[212:215], v[0:3]
	v_mfma_f32_16x16x32_bf16 v[30:33], v[148:151], v[192:195], v[30:33]
	v_mfma_f32_16x16x32_bf16 v[26:29], v[156:159], v[192:195], v[26:29]
	v_mfma_f32_16x16x32_bf16 v[22:25], v[148:151], v[200:203], v[22:25]
	v_mfma_f32_16x16x32_bf16 v[18:21], v[156:159], v[200:203], v[18:21]
	v_mfma_f32_16x16x32_bf16 v[12:15], v[148:151], v[208:211], v[12:15]
	v_mfma_f32_16x16x32_bf16 v[8:11], v[156:159], v[208:211], v[8:11]
	v_mfma_f32_16x16x32_bf16 v[4:7], v[148:151], v[230:233], v[4:7]
	v_mfma_f32_16x16x32_bf16 v[0:3], v[156:159], v[230:233], v[0:3]
	v_mfma_f32_16x16x32_bf16 v[94:97], v[160:163], v[188:191], v[94:97]
	v_mfma_f32_16x16x32_bf16 v[90:93], v[180:183], v[188:191], v[90:93]
	v_mfma_f32_16x16x32_bf16 v[86:89], v[160:163], v[196:199], v[86:89]
	v_mfma_f32_16x16x32_bf16 v[82:85], v[180:183], v[196:199], v[82:85]
	v_mfma_f32_16x16x32_bf16 v[78:81], v[160:163], v[204:207], v[78:81]
	v_mfma_f32_16x16x32_bf16 v[74:77], v[180:183], v[204:207], v[74:77]
	v_mfma_f32_16x16x32_bf16 v[70:73], v[160:163], v[212:215], v[70:73]
	v_mfma_f32_16x16x32_bf16 v[50:53], v[180:183], v[212:215], v[50:53]
	v_mfma_f32_16x16x32_bf16 v[94:97], v[176:179], v[192:195], v[94:97]
	v_mfma_f32_16x16x32_bf16 v[90:93], v[184:187], v[192:195], v[90:93]
	v_mfma_f32_16x16x32_bf16 v[86:89], v[176:179], v[200:203], v[86:89]
	v_mfma_f32_16x16x32_bf16 v[82:85], v[184:187], v[200:203], v[82:85]
	v_mfma_f32_16x16x32_bf16 v[78:81], v[176:179], v[208:211], v[78:81]
	v_mfma_f32_16x16x32_bf16 v[74:77], v[184:187], v[208:211], v[74:77]
	v_mfma_f32_16x16x32_bf16 v[70:73], v[176:179], v[230:233], v[70:73]
	v_mfma_f32_16x16x32_bf16 v[50:53], v[184:187], v[230:233], v[50:53]
	s_barrier
	s_add_i32 s63, 0, 0x18000
	v_add_u32_e32 v16, s63, v166
	s_add_i32 s64, 0, 0x1c000
	ds_read_b128 v[144:147], v16
	ds_read_b128 v[148:151], v16 offset:1024
	ds_read_b128 v[152:155], v16 offset:2048
	ds_read_b128 v[156:159], v16 offset:3072
	v_add_u32_e32 v16, s64, v166
	ds_read_b128 v[160:163], v16
	ds_read_b128 v[176:179], v16 offset:1024
	ds_read_b128 v[180:183], v16 offset:2048
	ds_read_b128 v[184:187], v16 offset:3072
	s_add_u32 s28, s28, 0x80000
	s_addc_u32 s29, s29, 0
	s_mov_b32 m0, s41
	v_lshl_add_u64 v[224:225], s[28:29], 0, v[130:131]
	ds_read_b128 v[188:191], v167 offset:32768
	ds_read_b128 v[192:195], v167 offset:33792
	ds_read_b128 v[196:199], v167 offset:34816
	ds_read_b128 v[200:203], v167 offset:35840
	ds_read_b128 v[204:207], v167 offset:36864
	ds_read_b128 v[208:211], v167 offset:37888
	ds_read_b128 v[212:215], v167 offset:38912
	ds_read_b128 v[230:233], v167 offset:39936
	global_load_lds_dwordx4 v[224:225], off
	v_lshl_add_u64 v[224:225], s[28:29], 0, v[134:135]
	s_mov_b32 m0, s42
	s_nop 0
	global_load_lds_dwordx4 v[224:225], off
	s_waitcnt vmcnt(8)
	s_waitcnt lgkmcnt(0)
	s_barrier
	s_waitcnt lgkmcnt(0)
	v_mfma_f32_16x16x32_bf16 v[66:69], v[144:147], v[188:191], v[66:69]
	v_mfma_f32_16x16x32_bf16 v[62:65], v[152:155], v[188:191], v[62:65]
	v_mfma_f32_16x16x32_bf16 v[58:61], v[144:147], v[196:199], v[58:61]
	v_mfma_f32_16x16x32_bf16 v[54:57], v[152:155], v[196:199], v[54:57]
	v_mfma_f32_16x16x32_bf16 v[46:49], v[144:147], v[204:207], v[46:49]
	v_mfma_f32_16x16x32_bf16 v[42:45], v[152:155], v[204:207], v[42:45]
	v_mfma_f32_16x16x32_bf16 v[38:41], v[144:147], v[212:215], v[38:41]
	v_mfma_f32_16x16x32_bf16 v[34:37], v[152:155], v[212:215], v[34:37]
	v_mfma_f32_16x16x32_bf16 v[66:69], v[148:151], v[192:195], v[66:69]
	v_mfma_f32_16x16x32_bf16 v[62:65], v[156:159], v[192:195], v[62:65]
	v_mfma_f32_16x16x32_bf16 v[58:61], v[148:151], v[200:203], v[58:61]
	v_mfma_f32_16x16x32_bf16 v[54:57], v[156:159], v[200:203], v[54:57]
	v_mfma_f32_16x16x32_bf16 v[46:49], v[148:151], v[208:211], v[46:49]
	v_mfma_f32_16x16x32_bf16 v[42:45], v[156:159], v[208:211], v[42:45]
	v_mfma_f32_16x16x32_bf16 v[38:41], v[148:151], v[230:233], v[38:41]
	v_mfma_f32_16x16x32_bf16 v[34:37], v[156:159], v[230:233], v[34:37]
	v_mfma_f32_16x16x32_bf16 v[126:129], v[160:163], v[188:191], v[126:129]
	v_mfma_f32_16x16x32_bf16 v[122:125], v[180:183], v[188:191], v[122:125]
	v_mfma_f32_16x16x32_bf16 v[118:121], v[160:163], v[196:199], v[118:121]
	v_mfma_f32_16x16x32_bf16 v[114:117], v[180:183], v[196:199], v[114:117]
	v_mfma_f32_16x16x32_bf16 v[110:113], v[160:163], v[204:207], v[110:113]
	v_mfma_f32_16x16x32_bf16 v[106:109], v[180:183], v[204:207], v[106:109]
	v_mfma_f32_16x16x32_bf16 v[102:105], v[160:163], v[212:215], v[102:105]
	v_mfma_f32_16x16x32_bf16 v[98:101], v[180:183], v[212:215], v[98:101]
	v_mfma_f32_16x16x32_bf16 v[126:129], v[176:179], v[192:195], v[126:129]
	v_mfma_f32_16x16x32_bf16 v[122:125], v[184:187], v[192:195], v[122:125]
	v_mfma_f32_16x16x32_bf16 v[118:121], v[176:179], v[200:203], v[118:121]
	v_mfma_f32_16x16x32_bf16 v[114:117], v[184:187], v[200:203], v[114:117]
	v_mfma_f32_16x16x32_bf16 v[110:113], v[176:179], v[208:211], v[110:113]
	v_mfma_f32_16x16x32_bf16 v[106:109], v[184:187], v[208:211], v[106:109]
	v_mfma_f32_16x16x32_bf16 v[102:105], v[176:179], v[230:233], v[102:105]
	v_mfma_f32_16x16x32_bf16 v[98:101], v[184:187], v[230:233], v[98:101]
	s_barrier
	s_add_i32 s28, s63, s38
	v_lshl_add_u64 v[168:169], v[168:169], 0, s[56:57]
	s_mov_b32 m0, s28
	ds_read_b128 v[188:191], v167 offset:49152
	ds_read_b128 v[192:195], v167 offset:50176
	ds_read_b128 v[196:199], v167 offset:51200
	ds_read_b128 v[200:203], v167 offset:52224
	ds_read_b128 v[204:207], v167 offset:53248
	ds_read_b128 v[208:211], v167 offset:54272
	ds_read_b128 v[212:215], v167 offset:55296
	ds_read_b128 v[230:233], v167 offset:56320
	global_load_lds_dwordx4 v[168:169], off
	s_add_i32 m0, s28, 0x2000
	s_add_u32 s26, s26, 0x80080
	v_lshl_add_u64 v[168:169], v[170:171], 0, s[56:57]
	s_addc_u32 s27, s27, 0
	s_add_i32 s28, s64, s38
	global_load_lds_dwordx4 v[168:169], off
	v_lshl_add_u64 v[168:169], s[26:27], 0, v[132:133]
	s_mov_b32 m0, s28
	s_nop 0
	global_load_lds_dwordx4 v[168:169], off
	v_lshl_add_u64 v[168:169], s[26:27], 0, v[136:137]
	s_add_i32 m0, s28, 0x2000
	s_nop 0
	global_load_lds_dwordx4 v[168:169], off
	v_lshl_add_u64 v[168:169], v[172:173], 0, s[56:57]
	s_mov_b32 m0, s46
	s_nop 0
	global_load_lds_dwordx4 v[168:169], off
	v_lshl_add_u64 v[168:169], v[222:223], 0, s[56:57]
	s_mov_b32 m0, s47
	s_nop 0
	global_load_lds_dwordx4 v[168:169], off
	s_waitcnt vmcnt(8)
	s_waitcnt lgkmcnt(0)
	s_barrier
	s_waitcnt lgkmcnt(0)
	v_mfma_f32_16x16x32_bf16 v[30:33], v[144:147], v[188:191], v[30:33]
	v_mfma_f32_16x16x32_bf16 v[26:29], v[152:155], v[188:191], v[26:29]
	v_mfma_f32_16x16x32_bf16 v[22:25], v[144:147], v[196:199], v[22:25]
	v_mfma_f32_16x16x32_bf16 v[18:21], v[152:155], v[196:199], v[18:21]
	v_mfma_f32_16x16x32_bf16 v[12:15], v[144:147], v[204:207], v[12:15]
	v_mfma_f32_16x16x32_bf16 v[8:11], v[152:155], v[204:207], v[8:11]
	v_mfma_f32_16x16x32_bf16 v[4:7], v[144:147], v[212:215], v[4:7]
	v_mfma_f32_16x16x32_bf16 v[0:3], v[152:155], v[212:215], v[0:3]
	v_mfma_f32_16x16x32_bf16 v[30:33], v[148:151], v[192:195], v[30:33]
	v_mfma_f32_16x16x32_bf16 v[26:29], v[156:159], v[192:195], v[26:29]
	v_mfma_f32_16x16x32_bf16 v[22:25], v[148:151], v[200:203], v[22:25]
	v_mfma_f32_16x16x32_bf16 v[18:21], v[156:159], v[200:203], v[18:21]
	v_mfma_f32_16x16x32_bf16 v[12:15], v[148:151], v[208:211], v[12:15]
	v_mfma_f32_16x16x32_bf16 v[8:11], v[156:159], v[208:211], v[8:11]
	v_mfma_f32_16x16x32_bf16 v[4:7], v[148:151], v[230:233], v[4:7]
	v_mfma_f32_16x16x32_bf16 v[0:3], v[156:159], v[230:233], v[0:3]
	v_mfma_f32_16x16x32_bf16 v[94:97], v[160:163], v[188:191], v[94:97]
	v_mfma_f32_16x16x32_bf16 v[90:93], v[180:183], v[188:191], v[90:93]
	v_mfma_f32_16x16x32_bf16 v[86:89], v[160:163], v[196:199], v[86:89]
	v_mfma_f32_16x16x32_bf16 v[82:85], v[180:183], v[196:199], v[82:85]
	v_mfma_f32_16x16x32_bf16 v[78:81], v[160:163], v[204:207], v[78:81]
	v_mfma_f32_16x16x32_bf16 v[74:77], v[180:183], v[204:207], v[74:77]
	v_mfma_f32_16x16x32_bf16 v[70:73], v[160:163], v[212:215], v[70:73]
	v_mfma_f32_16x16x32_bf16 v[50:53], v[180:183], v[212:215], v[50:53]
	v_mfma_f32_16x16x32_bf16 v[94:97], v[176:179], v[192:195], v[94:97]
	v_mfma_f32_16x16x32_bf16 v[90:93], v[184:187], v[192:195], v[90:93]
	v_mfma_f32_16x16x32_bf16 v[86:89], v[176:179], v[200:203], v[86:89]
	v_mfma_f32_16x16x32_bf16 v[82:85], v[184:187], v[200:203], v[82:85]
	v_mfma_f32_16x16x32_bf16 v[78:81], v[176:179], v[208:211], v[78:81]
	v_mfma_f32_16x16x32_bf16 v[74:77], v[184:187], v[208:211], v[74:77]
	v_mfma_f32_16x16x32_bf16 v[70:73], v[176:179], v[230:233], v[70:73]
	v_mfma_f32_16x16x32_bf16 v[50:53], v[184:187], v[230:233], v[50:53]
	s_barrier
	s_add_i32 s62, s62, 2
	s_add_u32 s24, s24, 0x100
	s_addc_u32 s25, s25, 0
	s_add_u32 s60, s60, 0x100
	s_addc_u32 s61, s61, 0
	s_cmp_gt_u32 s62, 29
	s_cbranch_scc0 .LBB0_1018
	s_setprio 0
	s_and_b64 vcc, exec, s[8:9]
	s_cbranch_vccz .LBB0_1021
	s_barrier

	.amdhsa_kernel _Z8mega_fwd4Args
		.amdhsa_group_segment_fixed_size 0
		.amdhsa_private_segment_fixed_size 0
		.amdhsa_kernarg_size 528
		.amdhsa_user_sgpr_count 2
		.amdhsa_user_sgpr_dispatch_ptr 0
		.amdhsa_user_sgpr_queue_ptr 0
		.amdhsa_user_sgpr_kernarg_segment_ptr 1
		.amdhsa_user_sgpr_dispatch_id 0
		.amdhsa_user_sgpr_kernarg_preload_length 0
		.amdhsa_user_sgpr_kernarg_preload_offset 0
		.amdhsa_user_sgpr_private_segment_size 0
		.amdhsa_uses_dynamic_stack 0
		.amdhsa_enable_private_segment 0
		.amdhsa_system_sgpr_workgroup_id_x 1
		.amdhsa_system_sgpr_workgroup_id_y 0
		.amdhsa_system_sgpr_workgroup_id_z 0
		.amdhsa_system_sgpr_workgroup_info 0
		.amdhsa_system_vgpr_workitem_id 2
		.amdhsa_next_free_vgpr 256
		.amdhsa_next_free_sgpr 102
		.amdhsa_accum_offset 256
		.amdhsa_reserve_vcc 1
		.amdhsa_float_round_mode_32 0
		.amdhsa_float_round_mode_16_64 0
		.amdhsa_float_denorm_mode_32 3
		.amdhsa_float_denorm_mode_16_64 3
		.amdhsa_dx10_clamp 1
		.amdhsa_ieee_mode 1
		.amdhsa_fp16_overflow 0
		.amdhsa_tg_split 0
		.amdhsa_exception_fp_ieee_invalid_op 0
		.amdhsa_exception_fp_denorm_src 0
		.amdhsa_exception_fp_ieee_div_zero 0
		.amdhsa_exception_fp_ieee_overflow 0
		.amdhsa_exception_fp_ieee_underflow 0
		.amdhsa_exception_fp_ieee_inexact 0
		.amdhsa_exception_int_div_zero 0
	.end_amdhsa_kernel

amdhsa.kernels:
  - .agpr_count:     0
    .args:
      - .offset:         0
        .size:           272
        .value_kind:     by_value
      - .offset:         272
        .size:           4
        .value_kind:     hidden_block_count_x
      - .offset:         276
        .size:           4
        .value_kind:     hidden_block_count_y
      - .offset:         280
        .size:           4
        .value_kind:     hidden_block_count_z
      - .offset:         284
        .size:           2
        .value_kind:     hidden_group_size_x
      - .offset:         286
        .size:           2
        .value_kind:     hidden_group_size_y
      - .offset:         288
        .size:           2
        .value_kind:     hidden_group_size_z
      - .offset:         290
        .size:           2
        .value_kind:     hidden_remainder_x
      - .offset:         292
        .size:           2
        .value_kind:     hidden_remainder_y
      - .offset:         294
        .size:           2
        .value_kind:     hidden_remainder_z
      - .offset:         312
        .size:           8
        .value_kind:     hidden_global_offset_x
      - .offset:         320
        .size:           8
        .value_kind:     hidden_global_offset_y
      - .offset:         328
        .size:           8
        .value_kind:     hidden_global_offset_z
      - .offset:         336
        .size:           2
        .value_kind:     hidden_grid_dims
      - .offset:         360
        .size:           8
        .value_kind:     hidden_multigrid_sync_arg
      - .offset:         392
        .size:           4
        .value_kind:     hidden_dynamic_lds_size
    .group_segment_fixed_size: 0
    .kernarg_segment_align: 8
    .kernarg_segment_size: 528
    .language:       OpenCL C
    .language_version:
      - 2
      - 0
    .max_flat_workgroup_size: 512
    .name:           _Z8mega_fwd4Args
    .private_segment_fixed_size: 0
    .sgpr_count:     108
    .sgpr_spill_count: 241
    .symbol:         _Z8mega_fwd4Args.kd
    .uniform_work_group_size: 1
    .uses_dynamic_stack: false
    .vgpr_count:     256
    .vgpr_spill_count: 0
    .wavefront_size: 64
